# phase-0 adaLN: staging and w_mod loads batched (34 + 64 loads in flight instead of 1 and 4), k-loop unrolled
# speedup vs baseline: 1.0109x; 1.0109x over previous
.LBB0_20:
	s_and_saveexec_b64 s[8:9], vcc
	s_cbranch_execz .LBB0_23
	s_mov_b64 s[10:11], s[54:55]
	global_load_dword v34, v3, s[10:11] offset:0
	global_load_dword v35, v3, s[10:11] offset:2048
	s_add_u32 s10, s10, 0x1000
	s_addc_u32 s11, s11, 0
	global_load_dword v36, v3, s[10:11] offset:0
	global_load_dword v37, v3, s[10:11] offset:2048
	s_add_u32 s10, s10, 0x1000
	s_addc_u32 s11, s11, 0
	global_load_dword v38, v3, s[10:11] offset:0
	global_load_dword v39, v3, s[10:11] offset:2048
	s_add_u32 s10, s10, 0x1000
	s_addc_u32 s11, s11, 0
	global_load_dword v40, v3, s[10:11] offset:0
	global_load_dword v41, v3, s[10:11] offset:2048
	s_add_u32 s10, s10, 0x1000
	s_addc_u32 s11, s11, 0
	global_load_dword v42, v3, s[10:11] offset:0
	global_load_dword v43, v3, s[10:11] offset:2048
	s_add_u32 s10, s10, 0x1000
	s_addc_u32 s11, s11, 0
	global_load_dword v44, v3, s[10:11] offset:0
	global_load_dword v45, v3, s[10:11] offset:2048
	s_add_u32 s10, s10, 0x1000
	s_addc_u32 s11, s11, 0
	global_load_dword v46, v3, s[10:11] offset:0
	global_load_dword v47, v3, s[10:11] offset:2048
	s_add_u32 s10, s10, 0x1000
	s_addc_u32 s11, s11, 0
	global_load_dword v48, v3, s[10:11] offset:0
	global_load_dword v49, v3, s[10:11] offset:2048
	s_add_u32 s10, s10, 0x1000
	s_addc_u32 s11, s11, 0
	global_load_dword v50, v3, s[10:11] offset:0
	global_load_dword v51, v3, s[10:11] offset:2048
	s_add_u32 s10, s10, 0x1000
	s_addc_u32 s11, s11, 0
	global_load_dword v52, v3, s[10:11] offset:0
	global_load_dword v53, v3, s[10:11] offset:2048
	s_add_u32 s10, s10, 0x1000
	s_addc_u32 s11, s11, 0
	global_load_dword v54, v3, s[10:11] offset:0
	global_load_dword v55, v3, s[10:11] offset:2048
	s_add_u32 s10, s10, 0x1000
	s_addc_u32 s11, s11, 0
	global_load_dword v56, v3, s[10:11] offset:0
	global_load_dword v57, v3, s[10:11] offset:2048
	s_add_u32 s10, s10, 0x1000
	s_addc_u32 s11, s11, 0
	global_load_dword v58, v3, s[10:11] offset:0
	global_load_dword v59, v3, s[10:11] offset:2048
	s_add_u32 s10, s10, 0x1000
	s_addc_u32 s11, s11, 0
	global_load_dword v60, v3, s[10:11] offset:0
	global_load_dword v61, v3, s[10:11] offset:2048
	s_add_u32 s10, s10, 0x1000
	s_addc_u32 s11, s11, 0
	global_load_dword v62, v3, s[10:11] offset:0
	global_load_dword v63, v3, s[10:11] offset:2048
	s_add_u32 s10, s10, 0x1000
	s_addc_u32 s11, s11, 0
	global_load_dword v64, v3, s[10:11] offset:0
	global_load_dword v65, v3, s[10:11] offset:2048
	s_add_u32 s10, s10, 0x1000
	s_addc_u32 s11, s11, 0
	global_load_dword v66, v3, s[58:59] offset:0
	global_load_dword v67, v3, s[58:59] offset:2048
	v_add_u32_e32 v16, 0x10000, v3
	s_waitcnt vmcnt(33)
	v_mul_f32_e32 v19, 0xbfb8aa3b, v34
	v_exp_f32_e32 v19, v19
	s_nop 0
	v_add_f32_e32 v17, 1.0, v19
	v_rcp_f32_e32 v19, v17
	s_nop 0
	v_mul_f32_e32 v0, v34, v19
	ds_write_b32 v3, v0 offset:0
	s_waitcnt vmcnt(32)
	v_mul_f32_e32 v19, 0xbfb8aa3b, v35
	v_exp_f32_e32 v19, v19
	s_nop 0
	v_add_f32_e32 v17, 1.0, v19
	v_rcp_f32_e32 v19, v17
	s_nop 0
	v_mul_f32_e32 v0, v35, v19
	ds_write_b32 v3, v0 offset:2048
	s_waitcnt vmcnt(31)
	v_mul_f32_e32 v19, 0xbfb8aa3b, v36
	v_exp_f32_e32 v19, v19
	s_nop 0
	v_add_f32_e32 v17, 1.0, v19
	v_rcp_f32_e32 v19, v17
	s_nop 0
	v_mul_f32_e32 v0, v36, v19
	ds_write_b32 v3, v0 offset:4096
	s_waitcnt vmcnt(30)
	v_mul_f32_e32 v19, 0xbfb8aa3b, v37
	v_exp_f32_e32 v19, v19
	s_nop 0
	v_add_f32_e32 v17, 1.0, v19
	v_rcp_f32_e32 v19, v17
	s_nop 0
	v_mul_f32_e32 v0, v37, v19
	ds_write_b32 v3, v0 offset:6144
	s_waitcnt vmcnt(29)
	v_mul_f32_e32 v19, 0xbfb8aa3b, v38
	v_exp_f32_e32 v19, v19
	s_nop 0
	v_add_f32_e32 v17, 1.0, v19
	v_rcp_f32_e32 v19, v17
	s_nop 0
	v_mul_f32_e32 v0, v38, v19
	ds_write_b32 v3, v0 offset:8192
	s_waitcnt vmcnt(28)
	v_mul_f32_e32 v19, 0xbfb8aa3b, v39
	v_exp_f32_e32 v19, v19
	s_nop 0
	v_add_f32_e32 v17, 1.0, v19
	v_rcp_f32_e32 v19, v17
	s_nop 0
	v_mul_f32_e32 v0, v39, v19
	ds_write_b32 v3, v0 offset:10240
	s_waitcnt vmcnt(27)
	v_mul_f32_e32 v19, 0xbfb8aa3b, v40
	v_exp_f32_e32 v19, v19
	s_nop 0
	v_add_f32_e32 v17, 1.0, v19
	v_rcp_f32_e32 v19, v17
	s_nop 0
	v_mul_f32_e32 v0, v40, v19
	ds_write_b32 v3, v0 offset:12288
	s_waitcnt vmcnt(26)
	v_mul_f32_e32 v19, 0xbfb8aa3b, v41
	v_exp_f32_e32 v19, v19
	s_nop 0
	v_add_f32_e32 v17, 1.0, v19
	v_rcp_f32_e32 v19, v17
	s_nop 0
	v_mul_f32_e32 v0, v41, v19
	ds_write_b32 v3, v0 offset:14336
	s_waitcnt vmcnt(25)
	v_mul_f32_e32 v19, 0xbfb8aa3b, v42
	v_exp_f32_e32 v19, v19
	s_nop 0
	v_add_f32_e32 v17, 1.0, v19
	v_rcp_f32_e32 v19, v17
	s_nop 0
	v_mul_f32_e32 v0, v42, v19
	ds_write_b32 v3, v0 offset:16384
	s_waitcnt vmcnt(24)
	v_mul_f32_e32 v19, 0xbfb8aa3b, v43
	v_exp_f32_e32 v19, v19
	s_nop 0
	v_add_f32_e32 v17, 1.0, v19
	v_rcp_f32_e32 v19, v17
	s_nop 0
	v_mul_f32_e32 v0, v43, v19
	ds_write_b32 v3, v0 offset:18432
	s_waitcnt vmcnt(23)
	v_mul_f32_e32 v19, 0xbfb8aa3b, v44
	v_exp_f32_e32 v19, v19
	s_nop 0
	v_add_f32_e32 v17, 1.0, v19
	v_rcp_f32_e32 v19, v17
	s_nop 0
	v_mul_f32_e32 v0, v44, v19
	ds_write_b32 v3, v0 offset:20480
	s_waitcnt vmcnt(22)
	v_mul_f32_e32 v19, 0xbfb8aa3b, v45
	v_exp_f32_e32 v19, v19
	s_nop 0
	v_add_f32_e32 v17, 1.0, v19
	v_rcp_f32_e32 v19, v17
	s_nop 0
	v_mul_f32_e32 v0, v45, v19
	ds_write_b32 v3, v0 offset:22528
	s_waitcnt vmcnt(21)
	v_mul_f32_e32 v19, 0xbfb8aa3b, v46
	v_exp_f32_e32 v19, v19
	s_nop 0
	v_add_f32_e32 v17, 1.0, v19
	v_rcp_f32_e32 v19, v17
	s_nop 0
	v_mul_f32_e32 v0, v46, v19
	ds_write_b32 v3, v0 offset:24576
	s_waitcnt vmcnt(20)
	v_mul_f32_e32 v19, 0xbfb8aa3b, v47
	v_exp_f32_e32 v19, v19
	s_nop 0
	v_add_f32_e32 v17, 1.0, v19
	v_rcp_f32_e32 v19, v17
	s_nop 0
	v_mul_f32_e32 v0, v47, v19
	ds_write_b32 v3, v0 offset:26624
	s_waitcnt vmcnt(19)
	v_mul_f32_e32 v19, 0xbfb8aa3b, v48
	v_exp_f32_e32 v19, v19
	s_nop 0
	v_add_f32_e32 v17, 1.0, v19
	v_rcp_f32_e32 v19, v17
	s_nop 0
	v_mul_f32_e32 v0, v48, v19
	ds_write_b32 v3, v0 offset:28672
	s_waitcnt vmcnt(18)
	v_mul_f32_e32 v19, 0xbfb8aa3b, v49
	v_exp_f32_e32 v19, v19
	s_nop 0
	v_add_f32_e32 v17, 1.0, v19
	v_rcp_f32_e32 v19, v17
	s_nop 0
	v_mul_f32_e32 v0, v49, v19
	ds_write_b32 v3, v0 offset:30720
	s_waitcnt vmcnt(17)
	v_mul_f32_e32 v19, 0xbfb8aa3b, v50
	v_exp_f32_e32 v19, v19
	s_nop 0
	v_add_f32_e32 v17, 1.0, v19
	v_rcp_f32_e32 v19, v17
	s_nop 0
	v_mul_f32_e32 v0, v50, v19
	ds_write_b32 v3, v0 offset:32768
	s_waitcnt vmcnt(16)
	v_mul_f32_e32 v19, 0xbfb8aa3b, v51
	v_exp_f32_e32 v19, v19
	s_nop 0
	v_add_f32_e32 v17, 1.0, v19
	v_rcp_f32_e32 v19, v17
	s_nop 0
	v_mul_f32_e32 v0, v51, v19
	ds_write_b32 v3, v0 offset:34816
	s_waitcnt vmcnt(15)
	v_mul_f32_e32 v19, 0xbfb8aa3b, v52
	v_exp_f32_e32 v19, v19
	s_nop 0
	v_add_f32_e32 v17, 1.0, v19
	v_rcp_f32_e32 v19, v17
	s_nop 0
	v_mul_f32_e32 v0, v52, v19
	ds_write_b32 v3, v0 offset:36864
	s_waitcnt vmcnt(14)
	v_mul_f32_e32 v19, 0xbfb8aa3b, v53
	v_exp_f32_e32 v19, v19
	s_nop 0
	v_add_f32_e32 v17, 1.0, v19
	v_rcp_f32_e32 v19, v17
	s_nop 0
	v_mul_f32_e32 v0, v53, v19
	ds_write_b32 v3, v0 offset:38912
	s_waitcnt vmcnt(13)
	v_mul_f32_e32 v19, 0xbfb8aa3b, v54
	v_exp_f32_e32 v19, v19
	s_nop 0
	v_add_f32_e32 v17, 1.0, v19
	v_rcp_f32_e32 v19, v17
	s_nop 0
	v_mul_f32_e32 v0, v54, v19
	ds_write_b32 v3, v0 offset:40960
	s_waitcnt vmcnt(12)
	v_mul_f32_e32 v19, 0xbfb8aa3b, v55
	v_exp_f32_e32 v19, v19
	s_nop 0
	v_add_f32_e32 v17, 1.0, v19
	v_rcp_f32_e32 v19, v17
	s_nop 0
	v_mul_f32_e32 v0, v55, v19
	ds_write_b32 v3, v0 offset:43008
	s_waitcnt vmcnt(11)
	v_mul_f32_e32 v19, 0xbfb8aa3b, v56
	v_exp_f32_e32 v19, v19
	s_nop 0
	v_add_f32_e32 v17, 1.0, v19
	v_rcp_f32_e32 v19, v17
	s_nop 0
	v_mul_f32_e32 v0, v56, v19
	ds_write_b32 v3, v0 offset:45056
	s_waitcnt vmcnt(10)
	v_mul_f32_e32 v19, 0xbfb8aa3b, v57
	v_exp_f32_e32 v19, v19
	s_nop 0
	v_add_f32_e32 v17, 1.0, v19
	v_rcp_f32_e32 v19, v17
	s_nop 0
	v_mul_f32_e32 v0, v57, v19
	ds_write_b32 v3, v0 offset:47104
	s_waitcnt vmcnt(9)
	v_mul_f32_e32 v19, 0xbfb8aa3b, v58
	v_exp_f32_e32 v19, v19
	s_nop 0
	v_add_f32_e32 v17, 1.0, v19
	v_rcp_f32_e32 v19, v17
	s_nop 0
	v_mul_f32_e32 v0, v58, v19
	ds_write_b32 v3, v0 offset:49152
	s_waitcnt vmcnt(8)
	v_mul_f32_e32 v19, 0xbfb8aa3b, v59
	v_exp_f32_e32 v19, v19
	s_nop 0
	v_add_f32_e32 v17, 1.0, v19
	v_rcp_f32_e32 v19, v17
	s_nop 0
	v_mul_f32_e32 v0, v59, v19
	ds_write_b32 v3, v0 offset:51200
	s_waitcnt vmcnt(7)
	v_mul_f32_e32 v19, 0xbfb8aa3b, v60
	v_exp_f32_e32 v19, v19
	s_nop 0
	v_add_f32_e32 v17, 1.0, v19
	v_rcp_f32_e32 v19, v17
	s_nop 0
	v_mul_f32_e32 v0, v60, v19
	ds_write_b32 v3, v0 offset:53248
	s_waitcnt vmcnt(6)
	v_mul_f32_e32 v19, 0xbfb8aa3b, v61
	v_exp_f32_e32 v19, v19
	s_nop 0
	v_add_f32_e32 v17, 1.0, v19
	v_rcp_f32_e32 v19, v17
	s_nop 0
	v_mul_f32_e32 v0, v61, v19
	ds_write_b32 v3, v0 offset:55296
	s_waitcnt vmcnt(5)
	v_mul_f32_e32 v19, 0xbfb8aa3b, v62
	v_exp_f32_e32 v19, v19
	s_nop 0
	v_add_f32_e32 v17, 1.0, v19
	v_rcp_f32_e32 v19, v17
	s_nop 0
	v_mul_f32_e32 v0, v62, v19
	ds_write_b32 v3, v0 offset:57344
	s_waitcnt vmcnt(4)
	v_mul_f32_e32 v19, 0xbfb8aa3b, v63
	v_exp_f32_e32 v19, v19
	s_nop 0
	v_add_f32_e32 v17, 1.0, v19
	v_rcp_f32_e32 v19, v17
	s_nop 0
	v_mul_f32_e32 v0, v63, v19
	ds_write_b32 v3, v0 offset:59392
	s_waitcnt vmcnt(3)
	v_mul_f32_e32 v19, 0xbfb8aa3b, v64
	v_exp_f32_e32 v19, v19
	s_nop 0
	v_add_f32_e32 v17, 1.0, v19
	v_rcp_f32_e32 v19, v17
	s_nop 0
	v_mul_f32_e32 v0, v64, v19
	ds_write_b32 v3, v0 offset:61440
	s_waitcnt vmcnt(2)
	v_mul_f32_e32 v19, 0xbfb8aa3b, v65
	v_exp_f32_e32 v19, v19
	s_nop 0
	v_add_f32_e32 v17, 1.0, v19
	v_rcp_f32_e32 v19, v17
	s_nop 0
	v_mul_f32_e32 v0, v65, v19
	ds_write_b32 v3, v0 offset:63488
	s_waitcnt vmcnt(1)
	v_mul_f32_e32 v19, 0xbfb8aa3b, v66
	v_exp_f32_e32 v19, v19
	s_nop 0
	v_add_f32_e32 v17, 1.0, v19
	v_rcp_f32_e32 v19, v17
	s_nop 0
	v_mul_f32_e32 v0, v66, v19
	ds_write_b32 v16, v0 offset:0
	s_waitcnt vmcnt(0)
	v_mul_f32_e32 v19, 0xbfb8aa3b, v67
	v_exp_f32_e32 v19, v19
	s_nop 0
	v_add_f32_e32 v17, 1.0, v19
	v_rcp_f32_e32 v19, v17
	s_nop 0
	v_mul_f32_e32 v0, v67, v19
	ds_write_b32 v16, v0 offset:2048
.LBB0_23:
	s_or_b64 exec, exec, s[8:9]
	s_mul_hi_i32 s0, s18, 0x2aaaaaab
	s_lshr_b32 s1, s0, 31
	s_ashr_i32 s19, s0, 4
	s_add_i32 s19, s19, s1
	s_mul_i32 s0, s19, 0x60
	s_sub_i32 s0, s18, s0
	s_lshl_b32 s8, s0, 5
	s_ashr_i32 s9, s8, 31
	s_mul_i32 s11, s19, 0xc00000
	s_lshl_b64 s[0:1], s[8:9], 2
	s_mul_hi_i32 s10, s19, 0xc00000
	s_add_u32 s0, s11, s0
	s_addc_u32 s1, s10, s1
	v_mov_b32_e32 v0, 0
	v_lshl_add_u64 v[14:15], v[12:13], 0, s[0:1]
	s_mov_b32 s10, 0
	v_mov_b32_e32 v16, 0
	v_mov_b32_e32 v17, v0
	v_mov_b32_e32 v18, 0
	v_mov_b32_e32 v19, v0
	v_mov_b32_e32 v20, 0
	v_mov_b32_e32 v21, v0
	v_mov_b32_e32 v22, 0
	v_mov_b32_e32 v23, v0
	v_mov_b32_e32 v24, 0
	v_mov_b32_e32 v25, v0
	v_mov_b32_e32 v26, 0
	v_mov_b32_e32 v27, v0
	v_mov_b32_e32 v28, 0
	v_mov_b32_e32 v29, v0
	v_mov_b32_e32 v30, 0
	v_mov_b32_e32 v31, v0
	s_waitcnt lgkmcnt(0)
	s_barrier
	v_add_co_u32_e64 v34, s[0:1], s15, v14
	s_nop 1
	v_addc_co_u32_e64 v35, s[0:1], -1, v15, s[0:1]
	s_mov_b64 s[0:1], 0x3000
	global_load_dword v126, v[34:35], off
	v_lshl_add_u64 v[34:35], v[34:35], 0, s[0:1]
	global_load_dword v127, v[34:35], off
	v_lshl_add_u64 v[34:35], v[34:35], 0, s[0:1]
	global_load_dword v128, v[34:35], off
	v_lshl_add_u64 v[34:35], v[34:35], 0, s[0:1]
	global_load_dword v129, v[34:35], off
	v_lshl_add_u64 v[34:35], v[34:35], 0, s[0:1]
	global_load_dword v130, v[34:35], off
	v_lshl_add_u64 v[34:35], v[34:35], 0, s[0:1]
	global_load_dword v131, v[34:35], off
	v_lshl_add_u64 v[34:35], v[34:35], 0, s[0:1]
	global_load_dword v132, v[34:35], off
	v_lshl_add_u64 v[34:35], v[34:35], 0, s[0:1]
	global_load_dword v133, v[34:35], off
	v_lshl_add_u64 v[34:35], v[34:35], 0, s[0:1]
	global_load_dword v134, v[34:35], off
	v_lshl_add_u64 v[34:35], v[34:35], 0, s[0:1]
	global_load_dword v135, v[34:35], off
	v_lshl_add_u64 v[34:35], v[34:35], 0, s[0:1]
	global_load_dword v136, v[34:35], off
	v_lshl_add_u64 v[34:35], v[34:35], 0, s[0:1]
	global_load_dword v137, v[34:35], off
	v_lshl_add_u64 v[34:35], v[34:35], 0, s[0:1]
	global_load_dword v138, v[34:35], off
	v_lshl_add_u64 v[34:35], v[34:35], 0, s[0:1]
	global_load_dword v139, v[34:35], off
	v_lshl_add_u64 v[34:35], v[34:35], 0, s[0:1]
	global_load_dword v140, v[34:35], off
	v_lshl_add_u64 v[34:35], v[34:35], 0, s[0:1]
	global_load_dword v141, v[34:35], off
	v_lshl_add_u64 v[34:35], v[34:35], 0, s[0:1]
	global_load_dword v142, v[34:35], off
	v_lshl_add_u64 v[34:35], v[34:35], 0, s[0:1]
	global_load_dword v143, v[34:35], off
	v_lshl_add_u64 v[34:35], v[34:35], 0, s[0:1]
	global_load_dword v144, v[34:35], off
	v_lshl_add_u64 v[34:35], v[34:35], 0, s[0:1]
	global_load_dword v145, v[34:35], off
	v_lshl_add_u64 v[34:35], v[34:35], 0, s[0:1]
	global_load_dword v146, v[34:35], off
	v_lshl_add_u64 v[34:35], v[34:35], 0, s[0:1]
	global_load_dword v147, v[34:35], off
	v_lshl_add_u64 v[34:35], v[34:35], 0, s[0:1]
	global_load_dword v148, v[34:35], off
	v_lshl_add_u64 v[34:35], v[34:35], 0, s[0:1]
	global_load_dword v149, v[34:35], off
	v_lshl_add_u64 v[34:35], v[34:35], 0, s[0:1]
	global_load_dword v150, v[34:35], off
	v_lshl_add_u64 v[34:35], v[34:35], 0, s[0:1]
	global_load_dword v151, v[34:35], off
	v_lshl_add_u64 v[34:35], v[34:35], 0, s[0:1]
	global_load_dword v152, v[34:35], off
	v_lshl_add_u64 v[34:35], v[34:35], 0, s[0:1]
	global_load_dword v153, v[34:35], off
	v_lshl_add_u64 v[34:35], v[34:35], 0, s[0:1]
	global_load_dword v154, v[34:35], off
	v_lshl_add_u64 v[34:35], v[34:35], 0, s[0:1]
	global_load_dword v155, v[34:35], off
	v_lshl_add_u64 v[34:35], v[34:35], 0, s[0:1]
	global_load_dword v156, v[34:35], off
	v_lshl_add_u64 v[34:35], v[34:35], 0, s[0:1]
	global_load_dword v157, v[34:35], off
	v_lshl_add_u64 v[34:35], v[34:35], 0, s[0:1]
	global_load_dword v158, v[34:35], off
	v_lshl_add_u64 v[34:35], v[34:35], 0, s[0:1]
	global_load_dword v159, v[34:35], off
	v_lshl_add_u64 v[34:35], v[34:35], 0, s[0:1]
	global_load_dword v160, v[34:35], off
	v_lshl_add_u64 v[34:35], v[34:35], 0, s[0:1]
	global_load_dword v161, v[34:35], off
	v_lshl_add_u64 v[34:35], v[34:35], 0, s[0:1]
	global_load_dword v162, v[34:35], off
	v_lshl_add_u64 v[34:35], v[34:35], 0, s[0:1]
	global_load_dword v163, v[34:35], off
	v_lshl_add_u64 v[34:35], v[34:35], 0, s[0:1]
	global_load_dword v164, v[34:35], off
	v_lshl_add_u64 v[34:35], v[34:35], 0, s[0:1]
	global_load_dword v165, v[34:35], off
	v_lshl_add_u64 v[34:35], v[34:35], 0, s[0:1]
	global_load_dword v166, v[34:35], off
	v_lshl_add_u64 v[34:35], v[34:35], 0, s[0:1]
	global_load_dword v167, v[34:35], off
	v_lshl_add_u64 v[34:35], v[34:35], 0, s[0:1]
	global_load_dword v168, v[34:35], off
	v_lshl_add_u64 v[34:35], v[34:35], 0, s[0:1]
	global_load_dword v169, v[34:35], off
	v_lshl_add_u64 v[34:35], v[34:35], 0, s[0:1]
	global_load_dword v170, v[34:35], off
	v_lshl_add_u64 v[34:35], v[34:35], 0, s[0:1]
	global_load_dword v171, v[34:35], off
	v_lshl_add_u64 v[34:35], v[34:35], 0, s[0:1]
	global_load_dword v172, v[34:35], off
	v_lshl_add_u64 v[34:35], v[34:35], 0, s[0:1]
	global_load_dword v173, v[34:35], off
	v_lshl_add_u64 v[34:35], v[34:35], 0, s[0:1]
	global_load_dword v174, v[34:35], off
	v_lshl_add_u64 v[34:35], v[34:35], 0, s[0:1]
	global_load_dword v175, v[34:35], off
	v_lshl_add_u64 v[34:35], v[34:35], 0, s[0:1]
	global_load_dword v176, v[34:35], off
	v_lshl_add_u64 v[34:35], v[34:35], 0, s[0:1]
	global_load_dword v177, v[34:35], off
	v_lshl_add_u64 v[34:35], v[34:35], 0, s[0:1]
	global_load_dword v178, v[34:35], off
	v_lshl_add_u64 v[34:35], v[34:35], 0, s[0:1]
	global_load_dword v179, v[34:35], off
	v_lshl_add_u64 v[34:35], v[34:35], 0, s[0:1]
	global_load_dword v180, v[34:35], off
	v_lshl_add_u64 v[34:35], v[34:35], 0, s[0:1]
	global_load_dword v181, v[34:35], off
	v_lshl_add_u64 v[34:35], v[34:35], 0, s[0:1]
	global_load_dword v182, v[34:35], off
	v_lshl_add_u64 v[34:35], v[34:35], 0, s[0:1]
	global_load_dword v183, v[34:35], off
	v_lshl_add_u64 v[34:35], v[34:35], 0, s[0:1]
	global_load_dword v184, v[34:35], off
	v_lshl_add_u64 v[34:35], v[34:35], 0, s[0:1]
	global_load_dword v185, v[34:35], off
	v_lshl_add_u64 v[34:35], v[34:35], 0, s[0:1]
	global_load_dword v186, v[34:35], off
	v_lshl_add_u64 v[34:35], v[34:35], 0, s[0:1]
	global_load_dword v187, v[34:35], off
	v_lshl_add_u64 v[34:35], v[34:35], 0, s[0:1]
	global_load_dword v188, v[34:35], off
	v_lshl_add_u64 v[34:35], v[34:35], 0, s[0:1]
	global_load_dword v189, v[34:35], off
	v_lshl_add_u64 v[34:35], v[34:35], 0, s[0:1]
	v_add_u32_e32 v98, s10, v5
	s_add_i32 s10, s10, 16
	ds_read_b128 v[34:37], v98
	ds_read_b128 v[38:41], v98 offset:4096
	ds_read_b128 v[42:45], v98 offset:8192
	ds_read_b128 v[46:49], v98 offset:12288
	ds_read_b128 v[50:53], v98 offset:16384
	ds_read_b128 v[54:57], v98 offset:20480
	ds_read_b128 v[58:61], v98 offset:24576
	ds_read_b128 v[62:65], v98 offset:28672
	ds_read_b128 v[66:69], v98 offset:32768
	ds_read_b128 v[70:73], v98 offset:36864
	ds_read_b128 v[74:77], v98 offset:40960
	ds_read_b128 v[78:81], v98 offset:45056
	ds_read_b128 v[82:85], v98 offset:49152
	ds_read_b128 v[86:89], v98 offset:53248
	ds_read_b128 v[90:93], v98 offset:57344
	ds_read_b128 v[94:97], v98 offset:61440
	v_add_u32_e32 v98, 0x10000, v98
	ds_read_b128 v[98:101], v98
	s_waitcnt lgkmcnt(14)
	v_mov_b32_e32 v110, v34
	v_mov_b32_e32 v111, v38
	v_mov_b32_e32 v112, v42
	s_waitcnt lgkmcnt(13)
	v_mov_b32_e32 v113, v46
	s_waitcnt lgkmcnt(12)
	v_mov_b32_e32 v114, v50
	s_waitcnt lgkmcnt(11)
	v_mov_b32_e32 v115, v54
	s_waitcnt lgkmcnt(10)
	v_mov_b32_e32 v116, v58
	s_waitcnt lgkmcnt(9)
	v_mov_b32_e32 v117, v62
	s_waitcnt lgkmcnt(8)
	v_mov_b32_e32 v118, v66
	s_waitcnt lgkmcnt(7)
	v_mov_b32_e32 v119, v70
	s_waitcnt lgkmcnt(6)
	v_mov_b32_e32 v120, v74
	s_waitcnt lgkmcnt(5)
	v_mov_b32_e32 v121, v78
	s_waitcnt lgkmcnt(4)
	v_mov_b32_e32 v122, v82
	s_waitcnt lgkmcnt(3)
	v_mov_b32_e32 v123, v86
	s_waitcnt lgkmcnt(2)
	v_mov_b32_e32 v124, v90
	s_waitcnt lgkmcnt(1)
	v_mov_b32_e32 v125, v94
	v_mov_b32_e32 v38, v35
	v_mov_b32_e32 v46, v43
	v_mov_b32_e32 v54, v51
	v_mov_b32_e32 v62, v59
	v_mov_b32_e32 v70, v67
	v_mov_b32_e32 v78, v75
	v_mov_b32_e32 v86, v83
	v_mov_b32_e32 v94, v91
	v_mov_b32_e32 v34, v36
	v_mov_b32_e32 v35, v40
	v_mov_b32_e32 v42, v44
	v_mov_b32_e32 v43, v48
	v_mov_b32_e32 v50, v52
	v_mov_b32_e32 v51, v56
	v_mov_b32_e32 v58, v60
	v_mov_b32_e32 v59, v64
	v_mov_b32_e32 v66, v68
	v_mov_b32_e32 v67, v72
	v_mov_b32_e32 v74, v76
	v_mov_b32_e32 v75, v80
	v_mov_b32_e32 v82, v84
	v_mov_b32_e32 v83, v88
	v_mov_b32_e32 v90, v92
	v_mov_b32_e32 v91, v96
	v_mov_b32_e32 v40, v37
	v_mov_b32_e32 v48, v45
	v_mov_b32_e32 v56, v53
	v_mov_b32_e32 v64, v61
	v_mov_b32_e32 v72, v69
	v_mov_b32_e32 v80, v77
	v_mov_b32_e32 v88, v85
	v_mov_b32_e32 v96, v93
	s_waitcnt vmcnt(63)
	v_pk_fma_f32 v[16:17], v[126:127], v[110:111], v[16:17] op_sel_hi:[0,1,1]
	v_pk_fma_f32 v[18:19], v[126:127], v[112:113], v[18:19] op_sel_hi:[0,1,1]
	v_pk_fma_f32 v[20:21], v[126:127], v[114:115], v[20:21] op_sel_hi:[0,1,1]
	v_pk_fma_f32 v[22:23], v[126:127], v[116:117], v[22:23] op_sel_hi:[0,1,1]
	v_pk_fma_f32 v[24:25], v[126:127], v[118:119], v[24:25] op_sel_hi:[0,1,1]
	v_pk_fma_f32 v[26:27], v[126:127], v[120:121], v[26:27] op_sel_hi:[0,1,1]
	v_pk_fma_f32 v[28:29], v[126:127], v[122:123], v[28:29] op_sel_hi:[0,1,1]
	v_pk_fma_f32 v[30:31], v[126:127], v[124:125], v[30:31] op_sel_hi:[0,1,1]
	s_waitcnt lgkmcnt(0)
	v_fmac_f32_e32 v0, v126, v98
	s_waitcnt vmcnt(62)
	v_pk_fma_f32 v[16:17], v[126:127], v[38:39], v[16:17] op_sel:[1,0,0] op_sel_hi:[1,1,1]
	v_pk_fma_f32 v[18:19], v[126:127], v[46:47], v[18:19] op_sel:[1,0,0] op_sel_hi:[1,1,1]
	v_pk_fma_f32 v[20:21], v[126:127], v[54:55], v[20:21] op_sel:[1,0,0] op_sel_hi:[1,1,1]
	v_pk_fma_f32 v[22:23], v[126:127], v[62:63], v[22:23] op_sel:[1,0,0] op_sel_hi:[1,1,1]
	v_pk_fma_f32 v[24:25], v[126:127], v[70:71], v[24:25] op_sel:[1,0,0] op_sel_hi:[1,1,1]
	v_pk_fma_f32 v[26:27], v[126:127], v[78:79], v[26:27] op_sel:[1,0,0] op_sel_hi:[1,1,1]
	v_pk_fma_f32 v[28:29], v[126:127], v[86:87], v[28:29] op_sel:[1,0,0] op_sel_hi:[1,1,1]
	v_pk_fma_f32 v[30:31], v[126:127], v[94:95], v[30:31] op_sel:[1,0,0] op_sel_hi:[1,1,1]
	v_fmac_f32_e32 v0, v127, v99
	s_waitcnt vmcnt(61)
	v_pk_fma_f32 v[16:17], v[128:129], v[34:35], v[16:17] op_sel_hi:[0,1,1]
	v_pk_fma_f32 v[18:19], v[128:129], v[42:43], v[18:19] op_sel_hi:[0,1,1]
	v_pk_fma_f32 v[20:21], v[128:129], v[50:51], v[20:21] op_sel_hi:[0,1,1]
	v_pk_fma_f32 v[22:23], v[128:129], v[58:59], v[22:23] op_sel_hi:[0,1,1]
	v_pk_fma_f32 v[24:25], v[128:129], v[66:67], v[24:25] op_sel_hi:[0,1,1]
	v_pk_fma_f32 v[26:27], v[128:129], v[74:75], v[26:27] op_sel_hi:[0,1,1]
	v_pk_fma_f32 v[28:29], v[128:129], v[82:83], v[28:29] op_sel_hi:[0,1,1]
	v_pk_fma_f32 v[30:31], v[128:129], v[90:91], v[30:31] op_sel_hi:[0,1,1]
	v_fmac_f32_e32 v0, v128, v100
	s_waitcnt vmcnt(60)
	v_pk_fma_f32 v[16:17], v[128:129], v[40:41], v[16:17] op_sel:[1,0,0] op_sel_hi:[1,1,1]
	v_pk_fma_f32 v[18:19], v[128:129], v[48:49], v[18:19] op_sel:[1,0,0] op_sel_hi:[1,1,1]
	v_pk_fma_f32 v[20:21], v[128:129], v[56:57], v[20:21] op_sel:[1,0,0] op_sel_hi:[1,1,1]
	v_pk_fma_f32 v[22:23], v[128:129], v[64:65], v[22:23] op_sel:[1,0,0] op_sel_hi:[1,1,1]
	v_pk_fma_f32 v[24:25], v[128:129], v[72:73], v[24:25] op_sel:[1,0,0] op_sel_hi:[1,1,1]
	v_pk_fma_f32 v[26:27], v[128:129], v[80:81], v[26:27] op_sel:[1,0,0] op_sel_hi:[1,1,1]
	v_pk_fma_f32 v[28:29], v[128:129], v[88:89], v[28:29] op_sel:[1,0,0] op_sel_hi:[1,1,1]
	v_pk_fma_f32 v[30:31], v[128:129], v[96:97], v[30:31] op_sel:[1,0,0] op_sel_hi:[1,1,1]
	v_fmac_f32_e32 v0, v129, v101
	v_add_u32_e32 v98, s10, v5
	s_add_i32 s10, s10, 16
	ds_read_b128 v[34:37], v98
	ds_read_b128 v[38:41], v98 offset:4096
	ds_read_b128 v[42:45], v98 offset:8192
	ds_read_b128 v[46:49], v98 offset:12288
	ds_read_b128 v[50:53], v98 offset:16384
	ds_read_b128 v[54:57], v98 offset:20480
	ds_read_b128 v[58:61], v98 offset:24576
	ds_read_b128 v[62:65], v98 offset:28672
	ds_read_b128 v[66:69], v98 offset:32768
	ds_read_b128 v[70:73], v98 offset:36864
	ds_read_b128 v[74:77], v98 offset:40960
	ds_read_b128 v[78:81], v98 offset:45056
	ds_read_b128 v[82:85], v98 offset:49152
	ds_read_b128 v[86:89], v98 offset:53248
	ds_read_b128 v[90:93], v98 offset:57344
	ds_read_b128 v[94:97], v98 offset:61440
	v_add_u32_e32 v98, 0x10000, v98
	ds_read_b128 v[98:101], v98
	s_waitcnt lgkmcnt(14)
	v_mov_b32_e32 v110, v34
	v_mov_b32_e32 v111, v38
	v_mov_b32_e32 v112, v42
	s_waitcnt lgkmcnt(13)
	v_mov_b32_e32 v113, v46
	s_waitcnt lgkmcnt(12)
	v_mov_b32_e32 v114, v50
	s_waitcnt lgkmcnt(11)
	v_mov_b32_e32 v115, v54
	s_waitcnt lgkmcnt(10)
	v_mov_b32_e32 v116, v58
	s_waitcnt lgkmcnt(9)
	v_mov_b32_e32 v117, v62
	s_waitcnt lgkmcnt(8)
	v_mov_b32_e32 v118, v66
	s_waitcnt lgkmcnt(7)
	v_mov_b32_e32 v119, v70
	s_waitcnt lgkmcnt(6)
	v_mov_b32_e32 v120, v74
	s_waitcnt lgkmcnt(5)
	v_mov_b32_e32 v121, v78
	s_waitcnt lgkmcnt(4)
	v_mov_b32_e32 v122, v82
	s_waitcnt lgkmcnt(3)
	v_mov_b32_e32 v123, v86
	s_waitcnt lgkmcnt(2)
	v_mov_b32_e32 v124, v90
	s_waitcnt lgkmcnt(1)
	v_mov_b32_e32 v125, v94
	v_mov_b32_e32 v38, v35
	v_mov_b32_e32 v46, v43
	v_mov_b32_e32 v54, v51
	v_mov_b32_e32 v62, v59
	v_mov_b32_e32 v70, v67
	v_mov_b32_e32 v78, v75
	v_mov_b32_e32 v86, v83
	v_mov_b32_e32 v94, v91
	v_mov_b32_e32 v34, v36
	v_mov_b32_e32 v35, v40
	v_mov_b32_e32 v42, v44
	v_mov_b32_e32 v43, v48
	v_mov_b32_e32 v50, v52
	v_mov_b32_e32 v51, v56
	v_mov_b32_e32 v58, v60
	v_mov_b32_e32 v59, v64
	v_mov_b32_e32 v66, v68
	v_mov_b32_e32 v67, v72
	v_mov_b32_e32 v74, v76
	v_mov_b32_e32 v75, v80
	v_mov_b32_e32 v82, v84
	v_mov_b32_e32 v83, v88
	v_mov_b32_e32 v90, v92
	v_mov_b32_e32 v91, v96
	v_mov_b32_e32 v40, v37
	v_mov_b32_e32 v48, v45
	v_mov_b32_e32 v56, v53
	v_mov_b32_e32 v64, v61
	v_mov_b32_e32 v72, v69
	v_mov_b32_e32 v80, v77
	v_mov_b32_e32 v88, v85
	v_mov_b32_e32 v96, v93
	s_waitcnt vmcnt(59)
	v_pk_fma_f32 v[16:17], v[130:131], v[110:111], v[16:17] op_sel_hi:[0,1,1]
	v_pk_fma_f32 v[18:19], v[130:131], v[112:113], v[18:19] op_sel_hi:[0,1,1]
	v_pk_fma_f32 v[20:21], v[130:131], v[114:115], v[20:21] op_sel_hi:[0,1,1]
	v_pk_fma_f32 v[22:23], v[130:131], v[116:117], v[22:23] op_sel_hi:[0,1,1]
	v_pk_fma_f32 v[24:25], v[130:131], v[118:119], v[24:25] op_sel_hi:[0,1,1]
	v_pk_fma_f32 v[26:27], v[130:131], v[120:121], v[26:27] op_sel_hi:[0,1,1]
	v_pk_fma_f32 v[28:29], v[130:131], v[122:123], v[28:29] op_sel_hi:[0,1,1]
	v_pk_fma_f32 v[30:31], v[130:131], v[124:125], v[30:31] op_sel_hi:[0,1,1]
	s_waitcnt lgkmcnt(0)
	v_fmac_f32_e32 v0, v130, v98
	s_waitcnt vmcnt(58)
	v_pk_fma_f32 v[16:17], v[130:131], v[38:39], v[16:17] op_sel:[1,0,0] op_sel_hi:[1,1,1]
	v_pk_fma_f32 v[18:19], v[130:131], v[46:47], v[18:19] op_sel:[1,0,0] op_sel_hi:[1,1,1]
	v_pk_fma_f32 v[20:21], v[130:131], v[54:55], v[20:21] op_sel:[1,0,0] op_sel_hi:[1,1,1]
	v_pk_fma_f32 v[22:23], v[130:131], v[62:63], v[22:23] op_sel:[1,0,0] op_sel_hi:[1,1,1]
	v_pk_fma_f32 v[24:25], v[130:131], v[70:71], v[24:25] op_sel:[1,0,0] op_sel_hi:[1,1,1]
	v_pk_fma_f32 v[26:27], v[130:131], v[78:79], v[26:27] op_sel:[1,0,0] op_sel_hi:[1,1,1]
	v_pk_fma_f32 v[28:29], v[130:131], v[86:87], v[28:29] op_sel:[1,0,0] op_sel_hi:[1,1,1]
	v_pk_fma_f32 v[30:31], v[130:131], v[94:95], v[30:31] op_sel:[1,0,0] op_sel_hi:[1,1,1]
	v_fmac_f32_e32 v0, v131, v99
	s_waitcnt vmcnt(57)
	v_pk_fma_f32 v[16:17], v[132:133], v[34:35], v[16:17] op_sel_hi:[0,1,1]
	v_pk_fma_f32 v[18:19], v[132:133], v[42:43], v[18:19] op_sel_hi:[0,1,1]
	v_pk_fma_f32 v[20:21], v[132:133], v[50:51], v[20:21] op_sel_hi:[0,1,1]
	v_pk_fma_f32 v[22:23], v[132:133], v[58:59], v[22:23] op_sel_hi:[0,1,1]
	v_pk_fma_f32 v[24:25], v[132:133], v[66:67], v[24:25] op_sel_hi:[0,1,1]
	v_pk_fma_f32 v[26:27], v[132:133], v[74:75], v[26:27] op_sel_hi:[0,1,1]
	v_pk_fma_f32 v[28:29], v[132:133], v[82:83], v[28:29] op_sel_hi:[0,1,1]
	v_pk_fma_f32 v[30:31], v[132:133], v[90:91], v[30:31] op_sel_hi:[0,1,1]
	v_fmac_f32_e32 v0, v132, v100
	s_waitcnt vmcnt(56)
	v_pk_fma_f32 v[16:17], v[132:133], v[40:41], v[16:17] op_sel:[1,0,0] op_sel_hi:[1,1,1]
	v_pk_fma_f32 v[18:19], v[132:133], v[48:49], v[18:19] op_sel:[1,0,0] op_sel_hi:[1,1,1]
	v_pk_fma_f32 v[20:21], v[132:133], v[56:57], v[20:21] op_sel:[1,0,0] op_sel_hi:[1,1,1]
	v_pk_fma_f32 v[22:23], v[132:133], v[64:65], v[22:23] op_sel:[1,0,0] op_sel_hi:[1,1,1]
	v_pk_fma_f32 v[24:25], v[132:133], v[72:73], v[24:25] op_sel:[1,0,0] op_sel_hi:[1,1,1]
	v_pk_fma_f32 v[26:27], v[132:133], v[80:81], v[26:27] op_sel:[1,0,0] op_sel_hi:[1,1,1]
	v_pk_fma_f32 v[28:29], v[132:133], v[88:89], v[28:29] op_sel:[1,0,0] op_sel_hi:[1,1,1]
	v_pk_fma_f32 v[30:31], v[132:133], v[96:97], v[30:31] op_sel:[1,0,0] op_sel_hi:[1,1,1]
	v_fmac_f32_e32 v0, v133, v101
	v_add_u32_e32 v98, s10, v5
	s_add_i32 s10, s10, 16
	ds_read_b128 v[34:37], v98
	ds_read_b128 v[38:41], v98 offset:4096
	ds_read_b128 v[42:45], v98 offset:8192
	ds_read_b128 v[46:49], v98 offset:12288
	ds_read_b128 v[50:53], v98 offset:16384
	ds_read_b128 v[54:57], v98 offset:20480
	ds_read_b128 v[58:61], v98 offset:24576
	ds_read_b128 v[62:65], v98 offset:28672
	ds_read_b128 v[66:69], v98 offset:32768
	ds_read_b128 v[70:73], v98 offset:36864
	ds_read_b128 v[74:77], v98 offset:40960
	ds_read_b128 v[78:81], v98 offset:45056
	ds_read_b128 v[82:85], v98 offset:49152
	ds_read_b128 v[86:89], v98 offset:53248
	ds_read_b128 v[90:93], v98 offset:57344
	ds_read_b128 v[94:97], v98 offset:61440
	v_add_u32_e32 v98, 0x10000, v98
	ds_read_b128 v[98:101], v98
	s_waitcnt lgkmcnt(14)
	v_mov_b32_e32 v110, v34
	v_mov_b32_e32 v111, v38
	v_mov_b32_e32 v112, v42
	s_waitcnt lgkmcnt(13)
	v_mov_b32_e32 v113, v46
	s_waitcnt lgkmcnt(12)
	v_mov_b32_e32 v114, v50
	s_waitcnt lgkmcnt(11)
	v_mov_b32_e32 v115, v54
	s_waitcnt lgkmcnt(10)
	v_mov_b32_e32 v116, v58
	s_waitcnt lgkmcnt(9)
	v_mov_b32_e32 v117, v62
	s_waitcnt lgkmcnt(8)
	v_mov_b32_e32 v118, v66
	s_waitcnt lgkmcnt(7)
	v_mov_b32_e32 v119, v70
	s_waitcnt lgkmcnt(6)
	v_mov_b32_e32 v120, v74
	s_waitcnt lgkmcnt(5)
	v_mov_b32_e32 v121, v78
	s_waitcnt lgkmcnt(4)
	v_mov_b32_e32 v122, v82
	s_waitcnt lgkmcnt(3)
	v_mov_b32_e32 v123, v86
	s_waitcnt lgkmcnt(2)
	v_mov_b32_e32 v124, v90
	s_waitcnt lgkmcnt(1)
	v_mov_b32_e32 v125, v94
	v_mov_b32_e32 v38, v35
	v_mov_b32_e32 v46, v43
	v_mov_b32_e32 v54, v51
	v_mov_b32_e32 v62, v59
	v_mov_b32_e32 v70, v67
	v_mov_b32_e32 v78, v75
	v_mov_b32_e32 v86, v83
	v_mov_b32_e32 v94, v91
	v_mov_b32_e32 v34, v36
	v_mov_b32_e32 v35, v40
	v_mov_b32_e32 v42, v44
	v_mov_b32_e32 v43, v48
	v_mov_b32_e32 v50, v52
	v_mov_b32_e32 v51, v56
	v_mov_b32_e32 v58, v60
	v_mov_b32_e32 v59, v64
	v_mov_b32_e32 v66, v68
	v_mov_b32_e32 v67, v72
	v_mov_b32_e32 v74, v76
	v_mov_b32_e32 v75, v80
	v_mov_b32_e32 v82, v84
	v_mov_b32_e32 v83, v88
	v_mov_b32_e32 v90, v92
	v_mov_b32_e32 v91, v96
	v_mov_b32_e32 v40, v37
	v_mov_b32_e32 v48, v45
	v_mov_b32_e32 v56, v53
	v_mov_b32_e32 v64, v61
	v_mov_b32_e32 v72, v69
	v_mov_b32_e32 v80, v77
	v_mov_b32_e32 v88, v85
	v_mov_b32_e32 v96, v93
	s_waitcnt vmcnt(55)
	v_pk_fma_f32 v[16:17], v[134:135], v[110:111], v[16:17] op_sel_hi:[0,1,1]
	v_pk_fma_f32 v[18:19], v[134:135], v[112:113], v[18:19] op_sel_hi:[0,1,1]
	v_pk_fma_f32 v[20:21], v[134:135], v[114:115], v[20:21] op_sel_hi:[0,1,1]
	v_pk_fma_f32 v[22:23], v[134:135], v[116:117], v[22:23] op_sel_hi:[0,1,1]
	v_pk_fma_f32 v[24:25], v[134:135], v[118:119], v[24:25] op_sel_hi:[0,1,1]
	v_pk_fma_f32 v[26:27], v[134:135], v[120:121], v[26:27] op_sel_hi:[0,1,1]
	v_pk_fma_f32 v[28:29], v[134:135], v[122:123], v[28:29] op_sel_hi:[0,1,1]
	v_pk_fma_f32 v[30:31], v[134:135], v[124:125], v[30:31] op_sel_hi:[0,1,1]
	s_waitcnt lgkmcnt(0)
	v_fmac_f32_e32 v0, v134, v98
	s_waitcnt vmcnt(54)
	v_pk_fma_f32 v[16:17], v[134:135], v[38:39], v[16:17] op_sel:[1,0,0] op_sel_hi:[1,1,1]
	v_pk_fma_f32 v[18:19], v[134:135], v[46:47], v[18:19] op_sel:[1,0,0] op_sel_hi:[1,1,1]
	v_pk_fma_f32 v[20:21], v[134:135], v[54:55], v[20:21] op_sel:[1,0,0] op_sel_hi:[1,1,1]
	v_pk_fma_f32 v[22:23], v[134:135], v[62:63], v[22:23] op_sel:[1,0,0] op_sel_hi:[1,1,1]
	v_pk_fma_f32 v[24:25], v[134:135], v[70:71], v[24:25] op_sel:[1,0,0] op_sel_hi:[1,1,1]
	v_pk_fma_f32 v[26:27], v[134:135], v[78:79], v[26:27] op_sel:[1,0,0] op_sel_hi:[1,1,1]
	v_pk_fma_f32 v[28:29], v[134:135], v[86:87], v[28:29] op_sel:[1,0,0] op_sel_hi:[1,1,1]
	v_pk_fma_f32 v[30:31], v[134:135], v[94:95], v[30:31] op_sel:[1,0,0] op_sel_hi:[1,1,1]
	v_fmac_f32_e32 v0, v135, v99
	s_waitcnt vmcnt(53)
	v_pk_fma_f32 v[16:17], v[136:137], v[34:35], v[16:17] op_sel_hi:[0,1,1]
	v_pk_fma_f32 v[18:19], v[136:137], v[42:43], v[18:19] op_sel_hi:[0,1,1]
	v_pk_fma_f32 v[20:21], v[136:137], v[50:51], v[20:21] op_sel_hi:[0,1,1]
	v_pk_fma_f32 v[22:23], v[136:137], v[58:59], v[22:23] op_sel_hi:[0,1,1]
	v_pk_fma_f32 v[24:25], v[136:137], v[66:67], v[24:25] op_sel_hi:[0,1,1]
	v_pk_fma_f32 v[26:27], v[136:137], v[74:75], v[26:27] op_sel_hi:[0,1,1]
	v_pk_fma_f32 v[28:29], v[136:137], v[82:83], v[28:29] op_sel_hi:[0,1,1]
	v_pk_fma_f32 v[30:31], v[136:137], v[90:91], v[30:31] op_sel_hi:[0,1,1]
	v_fmac_f32_e32 v0, v136, v100
	s_waitcnt vmcnt(52)
	v_pk_fma_f32 v[16:17], v[136:137], v[40:41], v[16:17] op_sel:[1,0,0] op_sel_hi:[1,1,1]
	v_pk_fma_f32 v[18:19], v[136:137], v[48:49], v[18:19] op_sel:[1,0,0] op_sel_hi:[1,1,1]
	v_pk_fma_f32 v[20:21], v[136:137], v[56:57], v[20:21] op_sel:[1,0,0] op_sel_hi:[1,1,1]
	v_pk_fma_f32 v[22:23], v[136:137], v[64:65], v[22:23] op_sel:[1,0,0] op_sel_hi:[1,1,1]
	v_pk_fma_f32 v[24:25], v[136:137], v[72:73], v[24:25] op_sel:[1,0,0] op_sel_hi:[1,1,1]
	v_pk_fma_f32 v[26:27], v[136:137], v[80:81], v[26:27] op_sel:[1,0,0] op_sel_hi:[1,1,1]
	v_pk_fma_f32 v[28:29], v[136:137], v[88:89], v[28:29] op_sel:[1,0,0] op_sel_hi:[1,1,1]
	v_pk_fma_f32 v[30:31], v[136:137], v[96:97], v[30:31] op_sel:[1,0,0] op_sel_hi:[1,1,1]
	v_fmac_f32_e32 v0, v137, v101
	v_add_u32_e32 v98, s10, v5
	s_add_i32 s10, s10, 16
	ds_read_b128 v[34:37], v98
	ds_read_b128 v[38:41], v98 offset:4096
	ds_read_b128 v[42:45], v98 offset:8192
	ds_read_b128 v[46:49], v98 offset:12288
	ds_read_b128 v[50:53], v98 offset:16384
	ds_read_b128 v[54:57], v98 offset:20480
	ds_read_b128 v[58:61], v98 offset:24576
	ds_read_b128 v[62:65], v98 offset:28672
	ds_read_b128 v[66:69], v98 offset:32768
	ds_read_b128 v[70:73], v98 offset:36864
	ds_read_b128 v[74:77], v98 offset:40960
	ds_read_b128 v[78:81], v98 offset:45056
	ds_read_b128 v[82:85], v98 offset:49152
	ds_read_b128 v[86:89], v98 offset:53248
	ds_read_b128 v[90:93], v98 offset:57344
	ds_read_b128 v[94:97], v98 offset:61440
	v_add_u32_e32 v98, 0x10000, v98
	ds_read_b128 v[98:101], v98
	s_waitcnt lgkmcnt(14)
	v_mov_b32_e32 v110, v34
	v_mov_b32_e32 v111, v38
	v_mov_b32_e32 v112, v42
	s_waitcnt lgkmcnt(13)
	v_mov_b32_e32 v113, v46
	s_waitcnt lgkmcnt(12)
	v_mov_b32_e32 v114, v50
	s_waitcnt lgkmcnt(11)
	v_mov_b32_e32 v115, v54
	s_waitcnt lgkmcnt(10)
	v_mov_b32_e32 v116, v58
	s_waitcnt lgkmcnt(9)
	v_mov_b32_e32 v117, v62
	s_waitcnt lgkmcnt(8)
	v_mov_b32_e32 v118, v66
	s_waitcnt lgkmcnt(7)
	v_mov_b32_e32 v119, v70
	s_waitcnt lgkmcnt(6)
	v_mov_b32_e32 v120, v74
	s_waitcnt lgkmcnt(5)
	v_mov_b32_e32 v121, v78
	s_waitcnt lgkmcnt(4)
	v_mov_b32_e32 v122, v82
	s_waitcnt lgkmcnt(3)
	v_mov_b32_e32 v123, v86
	s_waitcnt lgkmcnt(2)
	v_mov_b32_e32 v124, v90
	s_waitcnt lgkmcnt(1)
	v_mov_b32_e32 v125, v94
	v_mov_b32_e32 v38, v35
	v_mov_b32_e32 v46, v43
	v_mov_b32_e32 v54, v51
	v_mov_b32_e32 v62, v59
	v_mov_b32_e32 v70, v67
	v_mov_b32_e32 v78, v75
	v_mov_b32_e32 v86, v83
	v_mov_b32_e32 v94, v91
	v_mov_b32_e32 v34, v36
	v_mov_b32_e32 v35, v40
	v_mov_b32_e32 v42, v44
	v_mov_b32_e32 v43, v48
	v_mov_b32_e32 v50, v52
	v_mov_b32_e32 v51, v56
	v_mov_b32_e32 v58, v60
	v_mov_b32_e32 v59, v64
	v_mov_b32_e32 v66, v68
	v_mov_b32_e32 v67, v72
	v_mov_b32_e32 v74, v76
	v_mov_b32_e32 v75, v80
	v_mov_b32_e32 v82, v84
	v_mov_b32_e32 v83, v88
	v_mov_b32_e32 v90, v92
	v_mov_b32_e32 v91, v96
	v_mov_b32_e32 v40, v37
	v_mov_b32_e32 v48, v45
	v_mov_b32_e32 v56, v53
	v_mov_b32_e32 v64, v61
	v_mov_b32_e32 v72, v69
	v_mov_b32_e32 v80, v77
	v_mov_b32_e32 v88, v85
	v_mov_b32_e32 v96, v93
	s_waitcnt vmcnt(51)
	v_pk_fma_f32 v[16:17], v[138:139], v[110:111], v[16:17] op_sel_hi:[0,1,1]
	v_pk_fma_f32 v[18:19], v[138:139], v[112:113], v[18:19] op_sel_hi:[0,1,1]
	v_pk_fma_f32 v[20:21], v[138:139], v[114:115], v[20:21] op_sel_hi:[0,1,1]
	v_pk_fma_f32 v[22:23], v[138:139], v[116:117], v[22:23] op_sel_hi:[0,1,1]
	v_pk_fma_f32 v[24:25], v[138:139], v[118:119], v[24:25] op_sel_hi:[0,1,1]
	v_pk_fma_f32 v[26:27], v[138:139], v[120:121], v[26:27] op_sel_hi:[0,1,1]
	v_pk_fma_f32 v[28:29], v[138:139], v[122:123], v[28:29] op_sel_hi:[0,1,1]
	v_pk_fma_f32 v[30:31], v[138:139], v[124:125], v[30:31] op_sel_hi:[0,1,1]
	s_waitcnt lgkmcnt(0)
	v_fmac_f32_e32 v0, v138, v98
	s_waitcnt vmcnt(50)
	v_pk_fma_f32 v[16:17], v[138:139], v[38:39], v[16:17] op_sel:[1,0,0] op_sel_hi:[1,1,1]
	v_pk_fma_f32 v[18:19], v[138:139], v[46:47], v[18:19] op_sel:[1,0,0] op_sel_hi:[1,1,1]
	v_pk_fma_f32 v[20:21], v[138:139], v[54:55], v[20:21] op_sel:[1,0,0] op_sel_hi:[1,1,1]
	v_pk_fma_f32 v[22:23], v[138:139], v[62:63], v[22:23] op_sel:[1,0,0] op_sel_hi:[1,1,1]
	v_pk_fma_f32 v[24:25], v[138:139], v[70:71], v[24:25] op_sel:[1,0,0] op_sel_hi:[1,1,1]
	v_pk_fma_f32 v[26:27], v[138:139], v[78:79], v[26:27] op_sel:[1,0,0] op_sel_hi:[1,1,1]
	v_pk_fma_f32 v[28:29], v[138:139], v[86:87], v[28:29] op_sel:[1,0,0] op_sel_hi:[1,1,1]
	v_pk_fma_f32 v[30:31], v[138:139], v[94:95], v[30:31] op_sel:[1,0,0] op_sel_hi:[1,1,1]
	v_fmac_f32_e32 v0, v139, v99
	s_waitcnt vmcnt(49)
	v_pk_fma_f32 v[16:17], v[140:141], v[34:35], v[16:17] op_sel_hi:[0,1,1]
	v_pk_fma_f32 v[18:19], v[140:141], v[42:43], v[18:19] op_sel_hi:[0,1,1]
	v_pk_fma_f32 v[20:21], v[140:141], v[50:51], v[20:21] op_sel_hi:[0,1,1]
	v_pk_fma_f32 v[22:23], v[140:141], v[58:59], v[22:23] op_sel_hi:[0,1,1]
	v_pk_fma_f32 v[24:25], v[140:141], v[66:67], v[24:25] op_sel_hi:[0,1,1]
	v_pk_fma_f32 v[26:27], v[140:141], v[74:75], v[26:27] op_sel_hi:[0,1,1]
	v_pk_fma_f32 v[28:29], v[140:141], v[82:83], v[28:29] op_sel_hi:[0,1,1]
	v_pk_fma_f32 v[30:31], v[140:141], v[90:91], v[30:31] op_sel_hi:[0,1,1]
	v_fmac_f32_e32 v0, v140, v100
	s_waitcnt vmcnt(48)
	v_pk_fma_f32 v[16:17], v[140:141], v[40:41], v[16:17] op_sel:[1,0,0] op_sel_hi:[1,1,1]
	v_pk_fma_f32 v[18:19], v[140:141], v[48:49], v[18:19] op_sel:[1,0,0] op_sel_hi:[1,1,1]
	v_pk_fma_f32 v[20:21], v[140:141], v[56:57], v[20:21] op_sel:[1,0,0] op_sel_hi:[1,1,1]
	v_pk_fma_f32 v[22:23], v[140:141], v[64:65], v[22:23] op_sel:[1,0,0] op_sel_hi:[1,1,1]
	v_pk_fma_f32 v[24:25], v[140:141], v[72:73], v[24:25] op_sel:[1,0,0] op_sel_hi:[1,1,1]
	v_pk_fma_f32 v[26:27], v[140:141], v[80:81], v[26:27] op_sel:[1,0,0] op_sel_hi:[1,1,1]
	v_pk_fma_f32 v[28:29], v[140:141], v[88:89], v[28:29] op_sel:[1,0,0] op_sel_hi:[1,1,1]
	v_pk_fma_f32 v[30:31], v[140:141], v[96:97], v[30:31] op_sel:[1,0,0] op_sel_hi:[1,1,1]
	v_fmac_f32_e32 v0, v141, v101
	v_add_u32_e32 v98, s10, v5
	s_add_i32 s10, s10, 16
	ds_read_b128 v[34:37], v98
	ds_read_b128 v[38:41], v98 offset:4096
	ds_read_b128 v[42:45], v98 offset:8192
	ds_read_b128 v[46:49], v98 offset:12288
	ds_read_b128 v[50:53], v98 offset:16384
	ds_read_b128 v[54:57], v98 offset:20480
	ds_read_b128 v[58:61], v98 offset:24576
	ds_read_b128 v[62:65], v98 offset:28672
	ds_read_b128 v[66:69], v98 offset:32768
	ds_read_b128 v[70:73], v98 offset:36864
	ds_read_b128 v[74:77], v98 offset:40960
	ds_read_b128 v[78:81], v98 offset:45056
	ds_read_b128 v[82:85], v98 offset:49152
	ds_read_b128 v[86:89], v98 offset:53248
	ds_read_b128 v[90:93], v98 offset:57344
	ds_read_b128 v[94:97], v98 offset:61440
	v_add_u32_e32 v98, 0x10000, v98
	ds_read_b128 v[98:101], v98
	s_waitcnt lgkmcnt(14)
	v_mov_b32_e32 v110, v34
	v_mov_b32_e32 v111, v38
	v_mov_b32_e32 v112, v42
	s_waitcnt lgkmcnt(13)
	v_mov_b32_e32 v113, v46
	s_waitcnt lgkmcnt(12)
	v_mov_b32_e32 v114, v50
	s_waitcnt lgkmcnt(11)
	v_mov_b32_e32 v115, v54
	s_waitcnt lgkmcnt(10)
	v_mov_b32_e32 v116, v58
	s_waitcnt lgkmcnt(9)
	v_mov_b32_e32 v117, v62
	s_waitcnt lgkmcnt(8)
	v_mov_b32_e32 v118, v66
	s_waitcnt lgkmcnt(7)
	v_mov_b32_e32 v119, v70
	s_waitcnt lgkmcnt(6)
	v_mov_b32_e32 v120, v74
	s_waitcnt lgkmcnt(5)
	v_mov_b32_e32 v121, v78
	s_waitcnt lgkmcnt(4)
	v_mov_b32_e32 v122, v82
	s_waitcnt lgkmcnt(3)
	v_mov_b32_e32 v123, v86
	s_waitcnt lgkmcnt(2)
	v_mov_b32_e32 v124, v90
	s_waitcnt lgkmcnt(1)
	v_mov_b32_e32 v125, v94
	v_mov_b32_e32 v38, v35
	v_mov_b32_e32 v46, v43
	v_mov_b32_e32 v54, v51
	v_mov_b32_e32 v62, v59
	v_mov_b32_e32 v70, v67
	v_mov_b32_e32 v78, v75
	v_mov_b32_e32 v86, v83
	v_mov_b32_e32 v94, v91
	v_mov_b32_e32 v34, v36
	v_mov_b32_e32 v35, v40
	v_mov_b32_e32 v42, v44
	v_mov_b32_e32 v43, v48
	v_mov_b32_e32 v50, v52
	v_mov_b32_e32 v51, v56
	v_mov_b32_e32 v58, v60
	v_mov_b32_e32 v59, v64
	v_mov_b32_e32 v66, v68
	v_mov_b32_e32 v67, v72
	v_mov_b32_e32 v74, v76
	v_mov_b32_e32 v75, v80
	v_mov_b32_e32 v82, v84
	v_mov_b32_e32 v83, v88
	v_mov_b32_e32 v90, v92
	v_mov_b32_e32 v91, v96
	v_mov_b32_e32 v40, v37
	v_mov_b32_e32 v48, v45
	v_mov_b32_e32 v56, v53
	v_mov_b32_e32 v64, v61
	v_mov_b32_e32 v72, v69
	v_mov_b32_e32 v80, v77
	v_mov_b32_e32 v88, v85
	v_mov_b32_e32 v96, v93
	s_waitcnt vmcnt(47)
	v_pk_fma_f32 v[16:17], v[142:143], v[110:111], v[16:17] op_sel_hi:[0,1,1]
	v_pk_fma_f32 v[18:19], v[142:143], v[112:113], v[18:19] op_sel_hi:[0,1,1]
	v_pk_fma_f32 v[20:21], v[142:143], v[114:115], v[20:21] op_sel_hi:[0,1,1]
	v_pk_fma_f32 v[22:23], v[142:143], v[116:117], v[22:23] op_sel_hi:[0,1,1]
	v_pk_fma_f32 v[24:25], v[142:143], v[118:119], v[24:25] op_sel_hi:[0,1,1]
	v_pk_fma_f32 v[26:27], v[142:143], v[120:121], v[26:27] op_sel_hi:[0,1,1]
	v_pk_fma_f32 v[28:29], v[142:143], v[122:123], v[28:29] op_sel_hi:[0,1,1]
	v_pk_fma_f32 v[30:31], v[142:143], v[124:125], v[30:31] op_sel_hi:[0,1,1]
	s_waitcnt lgkmcnt(0)
	v_fmac_f32_e32 v0, v142, v98
	s_waitcnt vmcnt(46)
	v_pk_fma_f32 v[16:17], v[142:143], v[38:39], v[16:17] op_sel:[1,0,0] op_sel_hi:[1,1,1]
	v_pk_fma_f32 v[18:19], v[142:143], v[46:47], v[18:19] op_sel:[1,0,0] op_sel_hi:[1,1,1]
	v_pk_fma_f32 v[20:21], v[142:143], v[54:55], v[20:21] op_sel:[1,0,0] op_sel_hi:[1,1,1]
	v_pk_fma_f32 v[22:23], v[142:143], v[62:63], v[22:23] op_sel:[1,0,0] op_sel_hi:[1,1,1]
	v_pk_fma_f32 v[24:25], v[142:143], v[70:71], v[24:25] op_sel:[1,0,0] op_sel_hi:[1,1,1]
	v_pk_fma_f32 v[26:27], v[142:143], v[78:79], v[26:27] op_sel:[1,0,0] op_sel_hi:[1,1,1]
	v_pk_fma_f32 v[28:29], v[142:143], v[86:87], v[28:29] op_sel:[1,0,0] op_sel_hi:[1,1,1]
	v_pk_fma_f32 v[30:31], v[142:143], v[94:95], v[30:31] op_sel:[1,0,0] op_sel_hi:[1,1,1]
	v_fmac_f32_e32 v0, v143, v99
	s_waitcnt vmcnt(45)
	v_pk_fma_f32 v[16:17], v[144:145], v[34:35], v[16:17] op_sel_hi:[0,1,1]
	v_pk_fma_f32 v[18:19], v[144:145], v[42:43], v[18:19] op_sel_hi:[0,1,1]
	v_pk_fma_f32 v[20:21], v[144:145], v[50:51], v[20:21] op_sel_hi:[0,1,1]
	v_pk_fma_f32 v[22:23], v[144:145], v[58:59], v[22:23] op_sel_hi:[0,1,1]
	v_pk_fma_f32 v[24:25], v[144:145], v[66:67], v[24:25] op_sel_hi:[0,1,1]
	v_pk_fma_f32 v[26:27], v[144:145], v[74:75], v[26:27] op_sel_hi:[0,1,1]
	v_pk_fma_f32 v[28:29], v[144:145], v[82:83], v[28:29] op_sel_hi:[0,1,1]
	v_pk_fma_f32 v[30:31], v[144:145], v[90:91], v[30:31] op_sel_hi:[0,1,1]
	v_fmac_f32_e32 v0, v144, v100
	s_waitcnt vmcnt(44)
	v_pk_fma_f32 v[16:17], v[144:145], v[40:41], v[16:17] op_sel:[1,0,0] op_sel_hi:[1,1,1]
	v_pk_fma_f32 v[18:19], v[144:145], v[48:49], v[18:19] op_sel:[1,0,0] op_sel_hi:[1,1,1]
	v_pk_fma_f32 v[20:21], v[144:145], v[56:57], v[20:21] op_sel:[1,0,0] op_sel_hi:[1,1,1]
	v_pk_fma_f32 v[22:23], v[144:145], v[64:65], v[22:23] op_sel:[1,0,0] op_sel_hi:[1,1,1]
	v_pk_fma_f32 v[24:25], v[144:145], v[72:73], v[24:25] op_sel:[1,0,0] op_sel_hi:[1,1,1]
	v_pk_fma_f32 v[26:27], v[144:145], v[80:81], v[26:27] op_sel:[1,0,0] op_sel_hi:[1,1,1]
	v_pk_fma_f32 v[28:29], v[144:145], v[88:89], v[28:29] op_sel:[1,0,0] op_sel_hi:[1,1,1]
	v_pk_fma_f32 v[30:31], v[144:145], v[96:97], v[30:31] op_sel:[1,0,0] op_sel_hi:[1,1,1]
	v_fmac_f32_e32 v0, v145, v101
	v_add_u32_e32 v98, s10, v5
	s_add_i32 s10, s10, 16
	ds_read_b128 v[34:37], v98
	ds_read_b128 v[38:41], v98 offset:4096
	ds_read_b128 v[42:45], v98 offset:8192
	ds_read_b128 v[46:49], v98 offset:12288
	ds_read_b128 v[50:53], v98 offset:16384
	ds_read_b128 v[54:57], v98 offset:20480
	ds_read_b128 v[58:61], v98 offset:24576
	ds_read_b128 v[62:65], v98 offset:28672
	ds_read_b128 v[66:69], v98 offset:32768
	ds_read_b128 v[70:73], v98 offset:36864
	ds_read_b128 v[74:77], v98 offset:40960
	ds_read_b128 v[78:81], v98 offset:45056
	ds_read_b128 v[82:85], v98 offset:49152
	ds_read_b128 v[86:89], v98 offset:53248
	ds_read_b128 v[90:93], v98 offset:57344
	ds_read_b128 v[94:97], v98 offset:61440
	v_add_u32_e32 v98, 0x10000, v98
	ds_read_b128 v[98:101], v98
	s_waitcnt lgkmcnt(14)
	v_mov_b32_e32 v110, v34
	v_mov_b32_e32 v111, v38
	v_mov_b32_e32 v112, v42
	s_waitcnt lgkmcnt(13)
	v_mov_b32_e32 v113, v46
	s_waitcnt lgkmcnt(12)
	v_mov_b32_e32 v114, v50
	s_waitcnt lgkmcnt(11)
	v_mov_b32_e32 v115, v54
	s_waitcnt lgkmcnt(10)
	v_mov_b32_e32 v116, v58
	s_waitcnt lgkmcnt(9)
	v_mov_b32_e32 v117, v62
	s_waitcnt lgkmcnt(8)
	v_mov_b32_e32 v118, v66
	s_waitcnt lgkmcnt(7)
	v_mov_b32_e32 v119, v70
	s_waitcnt lgkmcnt(6)
	v_mov_b32_e32 v120, v74
	s_waitcnt lgkmcnt(5)
	v_mov_b32_e32 v121, v78
	s_waitcnt lgkmcnt(4)
	v_mov_b32_e32 v122, v82
	s_waitcnt lgkmcnt(3)
	v_mov_b32_e32 v123, v86
	s_waitcnt lgkmcnt(2)
	v_mov_b32_e32 v124, v90
	s_waitcnt lgkmcnt(1)
	v_mov_b32_e32 v125, v94
	v_mov_b32_e32 v38, v35
	v_mov_b32_e32 v46, v43
	v_mov_b32_e32 v54, v51
	v_mov_b32_e32 v62, v59
	v_mov_b32_e32 v70, v67
	v_mov_b32_e32 v78, v75
	v_mov_b32_e32 v86, v83
	v_mov_b32_e32 v94, v91
	v_mov_b32_e32 v34, v36
	v_mov_b32_e32 v35, v40
	v_mov_b32_e32 v42, v44
	v_mov_b32_e32 v43, v48
	v_mov_b32_e32 v50, v52
	v_mov_b32_e32 v51, v56
	v_mov_b32_e32 v58, v60
	v_mov_b32_e32 v59, v64
	v_mov_b32_e32 v66, v68
	v_mov_b32_e32 v67, v72
	v_mov_b32_e32 v74, v76
	v_mov_b32_e32 v75, v80
	v_mov_b32_e32 v82, v84
	v_mov_b32_e32 v83, v88
	v_mov_b32_e32 v90, v92
	v_mov_b32_e32 v91, v96
	v_mov_b32_e32 v40, v37
	v_mov_b32_e32 v48, v45
	v_mov_b32_e32 v56, v53
	v_mov_b32_e32 v64, v61
	v_mov_b32_e32 v72, v69
	v_mov_b32_e32 v80, v77
	v_mov_b32_e32 v88, v85
	v_mov_b32_e32 v96, v93
	s_waitcnt vmcnt(43)
	v_pk_fma_f32 v[16:17], v[146:147], v[110:111], v[16:17] op_sel_hi:[0,1,1]
	v_pk_fma_f32 v[18:19], v[146:147], v[112:113], v[18:19] op_sel_hi:[0,1,1]
	v_pk_fma_f32 v[20:21], v[146:147], v[114:115], v[20:21] op_sel_hi:[0,1,1]
	v_pk_fma_f32 v[22:23], v[146:147], v[116:117], v[22:23] op_sel_hi:[0,1,1]
	v_pk_fma_f32 v[24:25], v[146:147], v[118:119], v[24:25] op_sel_hi:[0,1,1]
	v_pk_fma_f32 v[26:27], v[146:147], v[120:121], v[26:27] op_sel_hi:[0,1,1]
	v_pk_fma_f32 v[28:29], v[146:147], v[122:123], v[28:29] op_sel_hi:[0,1,1]
	v_pk_fma_f32 v[30:31], v[146:147], v[124:125], v[30:31] op_sel_hi:[0,1,1]
	s_waitcnt lgkmcnt(0)
	v_fmac_f32_e32 v0, v146, v98
	s_waitcnt vmcnt(42)
	v_pk_fma_f32 v[16:17], v[146:147], v[38:39], v[16:17] op_sel:[1,0,0] op_sel_hi:[1,1,1]
	v_pk_fma_f32 v[18:19], v[146:147], v[46:47], v[18:19] op_sel:[1,0,0] op_sel_hi:[1,1,1]
	v_pk_fma_f32 v[20:21], v[146:147], v[54:55], v[20:21] op_sel:[1,0,0] op_sel_hi:[1,1,1]
	v_pk_fma_f32 v[22:23], v[146:147], v[62:63], v[22:23] op_sel:[1,0,0] op_sel_hi:[1,1,1]
	v_pk_fma_f32 v[24:25], v[146:147], v[70:71], v[24:25] op_sel:[1,0,0] op_sel_hi:[1,1,1]
	v_pk_fma_f32 v[26:27], v[146:147], v[78:79], v[26:27] op_sel:[1,0,0] op_sel_hi:[1,1,1]
	v_pk_fma_f32 v[28:29], v[146:147], v[86:87], v[28:29] op_sel:[1,0,0] op_sel_hi:[1,1,1]
	v_pk_fma_f32 v[30:31], v[146:147], v[94:95], v[30:31] op_sel:[1,0,0] op_sel_hi:[1,1,1]
	v_fmac_f32_e32 v0, v147, v99
	s_waitcnt vmcnt(41)
	v_pk_fma_f32 v[16:17], v[148:149], v[34:35], v[16:17] op_sel_hi:[0,1,1]
	v_pk_fma_f32 v[18:19], v[148:149], v[42:43], v[18:19] op_sel_hi:[0,1,1]
	v_pk_fma_f32 v[20:21], v[148:149], v[50:51], v[20:21] op_sel_hi:[0,1,1]
	v_pk_fma_f32 v[22:23], v[148:149], v[58:59], v[22:23] op_sel_hi:[0,1,1]
	v_pk_fma_f32 v[24:25], v[148:149], v[66:67], v[24:25] op_sel_hi:[0,1,1]
	v_pk_fma_f32 v[26:27], v[148:149], v[74:75], v[26:27] op_sel_hi:[0,1,1]
	v_pk_fma_f32 v[28:29], v[148:149], v[82:83], v[28:29] op_sel_hi:[0,1,1]
	v_pk_fma_f32 v[30:31], v[148:149], v[90:91], v[30:31] op_sel_hi:[0,1,1]
	v_fmac_f32_e32 v0, v148, v100
	s_waitcnt vmcnt(40)
	v_pk_fma_f32 v[16:17], v[148:149], v[40:41], v[16:17] op_sel:[1,0,0] op_sel_hi:[1,1,1]
	v_pk_fma_f32 v[18:19], v[148:149], v[48:49], v[18:19] op_sel:[1,0,0] op_sel_hi:[1,1,1]
	v_pk_fma_f32 v[20:21], v[148:149], v[56:57], v[20:21] op_sel:[1,0,0] op_sel_hi:[1,1,1]
	v_pk_fma_f32 v[22:23], v[148:149], v[64:65], v[22:23] op_sel:[1,0,0] op_sel_hi:[1,1,1]
	v_pk_fma_f32 v[24:25], v[148:149], v[72:73], v[24:25] op_sel:[1,0,0] op_sel_hi:[1,1,1]
	v_pk_fma_f32 v[26:27], v[148:149], v[80:81], v[26:27] op_sel:[1,0,0] op_sel_hi:[1,1,1]
	v_pk_fma_f32 v[28:29], v[148:149], v[88:89], v[28:29] op_sel:[1,0,0] op_sel_hi:[1,1,1]
	v_pk_fma_f32 v[30:31], v[148:149], v[96:97], v[30:31] op_sel:[1,0,0] op_sel_hi:[1,1,1]
	v_fmac_f32_e32 v0, v149, v101
	v_add_u32_e32 v98, s10, v5
	s_add_i32 s10, s10, 16
	ds_read_b128 v[34:37], v98
	ds_read_b128 v[38:41], v98 offset:4096
	ds_read_b128 v[42:45], v98 offset:8192
	ds_read_b128 v[46:49], v98 offset:12288
	ds_read_b128 v[50:53], v98 offset:16384
	ds_read_b128 v[54:57], v98 offset:20480
	ds_read_b128 v[58:61], v98 offset:24576
	ds_read_b128 v[62:65], v98 offset:28672
	ds_read_b128 v[66:69], v98 offset:32768
	ds_read_b128 v[70:73], v98 offset:36864
	ds_read_b128 v[74:77], v98 offset:40960
	ds_read_b128 v[78:81], v98 offset:45056
	ds_read_b128 v[82:85], v98 offset:49152
	ds_read_b128 v[86:89], v98 offset:53248
	ds_read_b128 v[90:93], v98 offset:57344
	ds_read_b128 v[94:97], v98 offset:61440
	v_add_u32_e32 v98, 0x10000, v98
	ds_read_b128 v[98:101], v98
	s_waitcnt lgkmcnt(14)
	v_mov_b32_e32 v110, v34
	v_mov_b32_e32 v111, v38
	v_mov_b32_e32 v112, v42
	s_waitcnt lgkmcnt(13)
	v_mov_b32_e32 v113, v46
	s_waitcnt lgkmcnt(12)
	v_mov_b32_e32 v114, v50
	s_waitcnt lgkmcnt(11)
	v_mov_b32_e32 v115, v54
	s_waitcnt lgkmcnt(10)
	v_mov_b32_e32 v116, v58
	s_waitcnt lgkmcnt(9)
	v_mov_b32_e32 v117, v62
	s_waitcnt lgkmcnt(8)
	v_mov_b32_e32 v118, v66
	s_waitcnt lgkmcnt(7)
	v_mov_b32_e32 v119, v70
	s_waitcnt lgkmcnt(6)
	v_mov_b32_e32 v120, v74
	s_waitcnt lgkmcnt(5)
	v_mov_b32_e32 v121, v78
	s_waitcnt lgkmcnt(4)
	v_mov_b32_e32 v122, v82
	s_waitcnt lgkmcnt(3)
	v_mov_b32_e32 v123, v86
	s_waitcnt lgkmcnt(2)
	v_mov_b32_e32 v124, v90
	s_waitcnt lgkmcnt(1)
	v_mov_b32_e32 v125, v94
	v_mov_b32_e32 v38, v35
	v_mov_b32_e32 v46, v43
	v_mov_b32_e32 v54, v51
	v_mov_b32_e32 v62, v59
	v_mov_b32_e32 v70, v67
	v_mov_b32_e32 v78, v75
	v_mov_b32_e32 v86, v83
	v_mov_b32_e32 v94, v91
	v_mov_b32_e32 v34, v36
	v_mov_b32_e32 v35, v40
	v_mov_b32_e32 v42, v44
	v_mov_b32_e32 v43, v48
	v_mov_b32_e32 v50, v52
	v_mov_b32_e32 v51, v56
	v_mov_b32_e32 v58, v60
	v_mov_b32_e32 v59, v64
	v_mov_b32_e32 v66, v68
	v_mov_b32_e32 v67, v72
	v_mov_b32_e32 v74, v76
	v_mov_b32_e32 v75, v80
	v_mov_b32_e32 v82, v84
	v_mov_b32_e32 v83, v88
	v_mov_b32_e32 v90, v92
	v_mov_b32_e32 v91, v96
	v_mov_b32_e32 v40, v37
	v_mov_b32_e32 v48, v45
	v_mov_b32_e32 v56, v53
	v_mov_b32_e32 v64, v61
	v_mov_b32_e32 v72, v69
	v_mov_b32_e32 v80, v77
	v_mov_b32_e32 v88, v85
	v_mov_b32_e32 v96, v93
	s_waitcnt vmcnt(39)
	v_pk_fma_f32 v[16:17], v[150:151], v[110:111], v[16:17] op_sel_hi:[0,1,1]
	v_pk_fma_f32 v[18:19], v[150:151], v[112:113], v[18:19] op_sel_hi:[0,1,1]
	v_pk_fma_f32 v[20:21], v[150:151], v[114:115], v[20:21] op_sel_hi:[0,1,1]
	v_pk_fma_f32 v[22:23], v[150:151], v[116:117], v[22:23] op_sel_hi:[0,1,1]
	v_pk_fma_f32 v[24:25], v[150:151], v[118:119], v[24:25] op_sel_hi:[0,1,1]
	v_pk_fma_f32 v[26:27], v[150:151], v[120:121], v[26:27] op_sel_hi:[0,1,1]
	v_pk_fma_f32 v[28:29], v[150:151], v[122:123], v[28:29] op_sel_hi:[0,1,1]
	v_pk_fma_f32 v[30:31], v[150:151], v[124:125], v[30:31] op_sel_hi:[0,1,1]
	s_waitcnt lgkmcnt(0)
	v_fmac_f32_e32 v0, v150, v98
	s_waitcnt vmcnt(38)
	v_pk_fma_f32 v[16:17], v[150:151], v[38:39], v[16:17] op_sel:[1,0,0] op_sel_hi:[1,1,1]
	v_pk_fma_f32 v[18:19], v[150:151], v[46:47], v[18:19] op_sel:[1,0,0] op_sel_hi:[1,1,1]
	v_pk_fma_f32 v[20:21], v[150:151], v[54:55], v[20:21] op_sel:[1,0,0] op_sel_hi:[1,1,1]
	v_pk_fma_f32 v[22:23], v[150:151], v[62:63], v[22:23] op_sel:[1,0,0] op_sel_hi:[1,1,1]
	v_pk_fma_f32 v[24:25], v[150:151], v[70:71], v[24:25] op_sel:[1,0,0] op_sel_hi:[1,1,1]
	v_pk_fma_f32 v[26:27], v[150:151], v[78:79], v[26:27] op_sel:[1,0,0] op_sel_hi:[1,1,1]
	v_pk_fma_f32 v[28:29], v[150:151], v[86:87], v[28:29] op_sel:[1,0,0] op_sel_hi:[1,1,1]
	v_pk_fma_f32 v[30:31], v[150:151], v[94:95], v[30:31] op_sel:[1,0,0] op_sel_hi:[1,1,1]
	v_fmac_f32_e32 v0, v151, v99
	s_waitcnt vmcnt(37)
	v_pk_fma_f32 v[16:17], v[152:153], v[34:35], v[16:17] op_sel_hi:[0,1,1]
	v_pk_fma_f32 v[18:19], v[152:153], v[42:43], v[18:19] op_sel_hi:[0,1,1]
	v_pk_fma_f32 v[20:21], v[152:153], v[50:51], v[20:21] op_sel_hi:[0,1,1]
	v_pk_fma_f32 v[22:23], v[152:153], v[58:59], v[22:23] op_sel_hi:[0,1,1]
	v_pk_fma_f32 v[24:25], v[152:153], v[66:67], v[24:25] op_sel_hi:[0,1,1]
	v_pk_fma_f32 v[26:27], v[152:153], v[74:75], v[26:27] op_sel_hi:[0,1,1]
	v_pk_fma_f32 v[28:29], v[152:153], v[82:83], v[28:29] op_sel_hi:[0,1,1]
	v_pk_fma_f32 v[30:31], v[152:153], v[90:91], v[30:31] op_sel_hi:[0,1,1]
	v_fmac_f32_e32 v0, v152, v100
	s_waitcnt vmcnt(36)
	v_pk_fma_f32 v[16:17], v[152:153], v[40:41], v[16:17] op_sel:[1,0,0] op_sel_hi:[1,1,1]
	v_pk_fma_f32 v[18:19], v[152:153], v[48:49], v[18:19] op_sel:[1,0,0] op_sel_hi:[1,1,1]
	v_pk_fma_f32 v[20:21], v[152:153], v[56:57], v[20:21] op_sel:[1,0,0] op_sel_hi:[1,1,1]
	v_pk_fma_f32 v[22:23], v[152:153], v[64:65], v[22:23] op_sel:[1,0,0] op_sel_hi:[1,1,1]
	v_pk_fma_f32 v[24:25], v[152:153], v[72:73], v[24:25] op_sel:[1,0,0] op_sel_hi:[1,1,1]
	v_pk_fma_f32 v[26:27], v[152:153], v[80:81], v[26:27] op_sel:[1,0,0] op_sel_hi:[1,1,1]
	v_pk_fma_f32 v[28:29], v[152:153], v[88:89], v[28:29] op_sel:[1,0,0] op_sel_hi:[1,1,1]
	v_pk_fma_f32 v[30:31], v[152:153], v[96:97], v[30:31] op_sel:[1,0,0] op_sel_hi:[1,1,1]
	v_fmac_f32_e32 v0, v153, v101
	v_add_u32_e32 v98, s10, v5
	s_add_i32 s10, s10, 16
	ds_read_b128 v[34:37], v98
	ds_read_b128 v[38:41], v98 offset:4096
	ds_read_b128 v[42:45], v98 offset:8192
	ds_read_b128 v[46:49], v98 offset:12288
	ds_read_b128 v[50:53], v98 offset:16384
	ds_read_b128 v[54:57], v98 offset:20480
	ds_read_b128 v[58:61], v98 offset:24576
	ds_read_b128 v[62:65], v98 offset:28672
	ds_read_b128 v[66:69], v98 offset:32768
	ds_read_b128 v[70:73], v98 offset:36864
	ds_read_b128 v[74:77], v98 offset:40960
	ds_read_b128 v[78:81], v98 offset:45056
	ds_read_b128 v[82:85], v98 offset:49152
	ds_read_b128 v[86:89], v98 offset:53248
	ds_read_b128 v[90:93], v98 offset:57344
	ds_read_b128 v[94:97], v98 offset:61440
	v_add_u32_e32 v98, 0x10000, v98
	ds_read_b128 v[98:101], v98
	s_waitcnt lgkmcnt(14)
	v_mov_b32_e32 v110, v34
	v_mov_b32_e32 v111, v38
	v_mov_b32_e32 v112, v42
	s_waitcnt lgkmcnt(13)
	v_mov_b32_e32 v113, v46
	s_waitcnt lgkmcnt(12)
	v_mov_b32_e32 v114, v50
	s_waitcnt lgkmcnt(11)
	v_mov_b32_e32 v115, v54
	s_waitcnt lgkmcnt(10)
	v_mov_b32_e32 v116, v58
	s_waitcnt lgkmcnt(9)
	v_mov_b32_e32 v117, v62
	s_waitcnt lgkmcnt(8)
	v_mov_b32_e32 v118, v66
	s_waitcnt lgkmcnt(7)
	v_mov_b32_e32 v119, v70
	s_waitcnt lgkmcnt(6)
	v_mov_b32_e32 v120, v74
	s_waitcnt lgkmcnt(5)
	v_mov_b32_e32 v121, v78
	s_waitcnt lgkmcnt(4)
	v_mov_b32_e32 v122, v82
	s_waitcnt lgkmcnt(3)
	v_mov_b32_e32 v123, v86
	s_waitcnt lgkmcnt(2)
	v_mov_b32_e32 v124, v90
	s_waitcnt lgkmcnt(1)
	v_mov_b32_e32 v125, v94
	v_mov_b32_e32 v38, v35
	v_mov_b32_e32 v46, v43
	v_mov_b32_e32 v54, v51
	v_mov_b32_e32 v62, v59
	v_mov_b32_e32 v70, v67
	v_mov_b32_e32 v78, v75
	v_mov_b32_e32 v86, v83
	v_mov_b32_e32 v94, v91
	v_mov_b32_e32 v34, v36
	v_mov_b32_e32 v35, v40
	v_mov_b32_e32 v42, v44
	v_mov_b32_e32 v43, v48
	v_mov_b32_e32 v50, v52
	v_mov_b32_e32 v51, v56
	v_mov_b32_e32 v58, v60
	v_mov_b32_e32 v59, v64
	v_mov_b32_e32 v66, v68
	v_mov_b32_e32 v67, v72
	v_mov_b32_e32 v74, v76
	v_mov_b32_e32 v75, v80
	v_mov_b32_e32 v82, v84
	v_mov_b32_e32 v83, v88
	v_mov_b32_e32 v90, v92
	v_mov_b32_e32 v91, v96
	v_mov_b32_e32 v40, v37
	v_mov_b32_e32 v48, v45
	v_mov_b32_e32 v56, v53
	v_mov_b32_e32 v64, v61
	v_mov_b32_e32 v72, v69
	v_mov_b32_e32 v80, v77
	v_mov_b32_e32 v88, v85
	v_mov_b32_e32 v96, v93
	s_waitcnt vmcnt(35)
	v_pk_fma_f32 v[16:17], v[154:155], v[110:111], v[16:17] op_sel_hi:[0,1,1]
	v_pk_fma_f32 v[18:19], v[154:155], v[112:113], v[18:19] op_sel_hi:[0,1,1]
	v_pk_fma_f32 v[20:21], v[154:155], v[114:115], v[20:21] op_sel_hi:[0,1,1]
	v_pk_fma_f32 v[22:23], v[154:155], v[116:117], v[22:23] op_sel_hi:[0,1,1]
	v_pk_fma_f32 v[24:25], v[154:155], v[118:119], v[24:25] op_sel_hi:[0,1,1]
	v_pk_fma_f32 v[26:27], v[154:155], v[120:121], v[26:27] op_sel_hi:[0,1,1]
	v_pk_fma_f32 v[28:29], v[154:155], v[122:123], v[28:29] op_sel_hi:[0,1,1]
	v_pk_fma_f32 v[30:31], v[154:155], v[124:125], v[30:31] op_sel_hi:[0,1,1]
	s_waitcnt lgkmcnt(0)
	v_fmac_f32_e32 v0, v154, v98
	s_waitcnt vmcnt(34)
	v_pk_fma_f32 v[16:17], v[154:155], v[38:39], v[16:17] op_sel:[1,0,0] op_sel_hi:[1,1,1]
	v_pk_fma_f32 v[18:19], v[154:155], v[46:47], v[18:19] op_sel:[1,0,0] op_sel_hi:[1,1,1]
	v_pk_fma_f32 v[20:21], v[154:155], v[54:55], v[20:21] op_sel:[1,0,0] op_sel_hi:[1,1,1]
	v_pk_fma_f32 v[22:23], v[154:155], v[62:63], v[22:23] op_sel:[1,0,0] op_sel_hi:[1,1,1]
	v_pk_fma_f32 v[24:25], v[154:155], v[70:71], v[24:25] op_sel:[1,0,0] op_sel_hi:[1,1,1]
	v_pk_fma_f32 v[26:27], v[154:155], v[78:79], v[26:27] op_sel:[1,0,0] op_sel_hi:[1,1,1]
	v_pk_fma_f32 v[28:29], v[154:155], v[86:87], v[28:29] op_sel:[1,0,0] op_sel_hi:[1,1,1]
	v_pk_fma_f32 v[30:31], v[154:155], v[94:95], v[30:31] op_sel:[1,0,0] op_sel_hi:[1,1,1]
	v_fmac_f32_e32 v0, v155, v99
	s_waitcnt vmcnt(33)
	v_pk_fma_f32 v[16:17], v[156:157], v[34:35], v[16:17] op_sel_hi:[0,1,1]
	v_pk_fma_f32 v[18:19], v[156:157], v[42:43], v[18:19] op_sel_hi:[0,1,1]
	v_pk_fma_f32 v[20:21], v[156:157], v[50:51], v[20:21] op_sel_hi:[0,1,1]
	v_pk_fma_f32 v[22:23], v[156:157], v[58:59], v[22:23] op_sel_hi:[0,1,1]
	v_pk_fma_f32 v[24:25], v[156:157], v[66:67], v[24:25] op_sel_hi:[0,1,1]
	v_pk_fma_f32 v[26:27], v[156:157], v[74:75], v[26:27] op_sel_hi:[0,1,1]
	v_pk_fma_f32 v[28:29], v[156:157], v[82:83], v[28:29] op_sel_hi:[0,1,1]
	v_pk_fma_f32 v[30:31], v[156:157], v[90:91], v[30:31] op_sel_hi:[0,1,1]
	v_fmac_f32_e32 v0, v156, v100
	s_waitcnt vmcnt(32)
	v_pk_fma_f32 v[16:17], v[156:157], v[40:41], v[16:17] op_sel:[1,0,0] op_sel_hi:[1,1,1]
	v_pk_fma_f32 v[18:19], v[156:157], v[48:49], v[18:19] op_sel:[1,0,0] op_sel_hi:[1,1,1]
	v_pk_fma_f32 v[20:21], v[156:157], v[56:57], v[20:21] op_sel:[1,0,0] op_sel_hi:[1,1,1]
	v_pk_fma_f32 v[22:23], v[156:157], v[64:65], v[22:23] op_sel:[1,0,0] op_sel_hi:[1,1,1]
	v_pk_fma_f32 v[24:25], v[156:157], v[72:73], v[24:25] op_sel:[1,0,0] op_sel_hi:[1,1,1]
	v_pk_fma_f32 v[26:27], v[156:157], v[80:81], v[26:27] op_sel:[1,0,0] op_sel_hi:[1,1,1]
	v_pk_fma_f32 v[28:29], v[156:157], v[88:89], v[28:29] op_sel:[1,0,0] op_sel_hi:[1,1,1]
	v_pk_fma_f32 v[30:31], v[156:157], v[96:97], v[30:31] op_sel:[1,0,0] op_sel_hi:[1,1,1]
	v_fmac_f32_e32 v0, v157, v101
	v_add_u32_e32 v98, s10, v5
	s_add_i32 s10, s10, 16
	ds_read_b128 v[34:37], v98
	ds_read_b128 v[38:41], v98 offset:4096
	ds_read_b128 v[42:45], v98 offset:8192
	ds_read_b128 v[46:49], v98 offset:12288
	ds_read_b128 v[50:53], v98 offset:16384
	ds_read_b128 v[54:57], v98 offset:20480
	ds_read_b128 v[58:61], v98 offset:24576
	ds_read_b128 v[62:65], v98 offset:28672
	ds_read_b128 v[66:69], v98 offset:32768
	ds_read_b128 v[70:73], v98 offset:36864
	ds_read_b128 v[74:77], v98 offset:40960
	ds_read_b128 v[78:81], v98 offset:45056
	ds_read_b128 v[82:85], v98 offset:49152
	ds_read_b128 v[86:89], v98 offset:53248
	ds_read_b128 v[90:93], v98 offset:57344
	ds_read_b128 v[94:97], v98 offset:61440
	v_add_u32_e32 v98, 0x10000, v98
	ds_read_b128 v[98:101], v98
	s_waitcnt lgkmcnt(14)
	v_mov_b32_e32 v110, v34
	v_mov_b32_e32 v111, v38
	v_mov_b32_e32 v112, v42
	s_waitcnt lgkmcnt(13)
	v_mov_b32_e32 v113, v46
	s_waitcnt lgkmcnt(12)
	v_mov_b32_e32 v114, v50
	s_waitcnt lgkmcnt(11)
	v_mov_b32_e32 v115, v54
	s_waitcnt lgkmcnt(10)
	v_mov_b32_e32 v116, v58
	s_waitcnt lgkmcnt(9)
	v_mov_b32_e32 v117, v62
	s_waitcnt lgkmcnt(8)
	v_mov_b32_e32 v118, v66
	s_waitcnt lgkmcnt(7)
	v_mov_b32_e32 v119, v70
	s_waitcnt lgkmcnt(6)
	v_mov_b32_e32 v120, v74
	s_waitcnt lgkmcnt(5)
	v_mov_b32_e32 v121, v78
	s_waitcnt lgkmcnt(4)
	v_mov_b32_e32 v122, v82
	s_waitcnt lgkmcnt(3)
	v_mov_b32_e32 v123, v86
	s_waitcnt lgkmcnt(2)
	v_mov_b32_e32 v124, v90
	s_waitcnt lgkmcnt(1)
	v_mov_b32_e32 v125, v94
	v_mov_b32_e32 v38, v35
	v_mov_b32_e32 v46, v43
	v_mov_b32_e32 v54, v51
	v_mov_b32_e32 v62, v59
	v_mov_b32_e32 v70, v67
	v_mov_b32_e32 v78, v75
	v_mov_b32_e32 v86, v83
	v_mov_b32_e32 v94, v91
	v_mov_b32_e32 v34, v36
	v_mov_b32_e32 v35, v40
	v_mov_b32_e32 v42, v44
	v_mov_b32_e32 v43, v48
	v_mov_b32_e32 v50, v52
	v_mov_b32_e32 v51, v56
	v_mov_b32_e32 v58, v60
	v_mov_b32_e32 v59, v64
	v_mov_b32_e32 v66, v68
	v_mov_b32_e32 v67, v72
	v_mov_b32_e32 v74, v76
	v_mov_b32_e32 v75, v80
	v_mov_b32_e32 v82, v84
	v_mov_b32_e32 v83, v88
	v_mov_b32_e32 v90, v92
	v_mov_b32_e32 v91, v96
	v_mov_b32_e32 v40, v37
	v_mov_b32_e32 v48, v45
	v_mov_b32_e32 v56, v53
	v_mov_b32_e32 v64, v61
	v_mov_b32_e32 v72, v69
	v_mov_b32_e32 v80, v77
	v_mov_b32_e32 v88, v85
	v_mov_b32_e32 v96, v93
	s_waitcnt vmcnt(31)
	v_pk_fma_f32 v[16:17], v[158:159], v[110:111], v[16:17] op_sel_hi:[0,1,1]
	v_pk_fma_f32 v[18:19], v[158:159], v[112:113], v[18:19] op_sel_hi:[0,1,1]
	v_pk_fma_f32 v[20:21], v[158:159], v[114:115], v[20:21] op_sel_hi:[0,1,1]
	v_pk_fma_f32 v[22:23], v[158:159], v[116:117], v[22:23] op_sel_hi:[0,1,1]
	v_pk_fma_f32 v[24:25], v[158:159], v[118:119], v[24:25] op_sel_hi:[0,1,1]
	v_pk_fma_f32 v[26:27], v[158:159], v[120:121], v[26:27] op_sel_hi:[0,1,1]
	v_pk_fma_f32 v[28:29], v[158:159], v[122:123], v[28:29] op_sel_hi:[0,1,1]
	v_pk_fma_f32 v[30:31], v[158:159], v[124:125], v[30:31] op_sel_hi:[0,1,1]
	s_waitcnt lgkmcnt(0)
	v_fmac_f32_e32 v0, v158, v98
	s_waitcnt vmcnt(30)
	v_pk_fma_f32 v[16:17], v[158:159], v[38:39], v[16:17] op_sel:[1,0,0] op_sel_hi:[1,1,1]
	v_pk_fma_f32 v[18:19], v[158:159], v[46:47], v[18:19] op_sel:[1,0,0] op_sel_hi:[1,1,1]
	v_pk_fma_f32 v[20:21], v[158:159], v[54:55], v[20:21] op_sel:[1,0,0] op_sel_hi:[1,1,1]
	v_pk_fma_f32 v[22:23], v[158:159], v[62:63], v[22:23] op_sel:[1,0,0] op_sel_hi:[1,1,1]
	v_pk_fma_f32 v[24:25], v[158:159], v[70:71], v[24:25] op_sel:[1,0,0] op_sel_hi:[1,1,1]
	v_pk_fma_f32 v[26:27], v[158:159], v[78:79], v[26:27] op_sel:[1,0,0] op_sel_hi:[1,1,1]
	v_pk_fma_f32 v[28:29], v[158:159], v[86:87], v[28:29] op_sel:[1,0,0] op_sel_hi:[1,1,1]
	v_pk_fma_f32 v[30:31], v[158:159], v[94:95], v[30:31] op_sel:[1,0,0] op_sel_hi:[1,1,1]
	v_fmac_f32_e32 v0, v159, v99
	s_waitcnt vmcnt(29)
	v_pk_fma_f32 v[16:17], v[160:161], v[34:35], v[16:17] op_sel_hi:[0,1,1]
	v_pk_fma_f32 v[18:19], v[160:161], v[42:43], v[18:19] op_sel_hi:[0,1,1]
	v_pk_fma_f32 v[20:21], v[160:161], v[50:51], v[20:21] op_sel_hi:[0,1,1]
	v_pk_fma_f32 v[22:23], v[160:161], v[58:59], v[22:23] op_sel_hi:[0,1,1]
	v_pk_fma_f32 v[24:25], v[160:161], v[66:67], v[24:25] op_sel_hi:[0,1,1]
	v_pk_fma_f32 v[26:27], v[160:161], v[74:75], v[26:27] op_sel_hi:[0,1,1]
	v_pk_fma_f32 v[28:29], v[160:161], v[82:83], v[28:29] op_sel_hi:[0,1,1]
	v_pk_fma_f32 v[30:31], v[160:161], v[90:91], v[30:31] op_sel_hi:[0,1,1]
	v_fmac_f32_e32 v0, v160, v100
	s_waitcnt vmcnt(28)
	v_pk_fma_f32 v[16:17], v[160:161], v[40:41], v[16:17] op_sel:[1,0,0] op_sel_hi:[1,1,1]
	v_pk_fma_f32 v[18:19], v[160:161], v[48:49], v[18:19] op_sel:[1,0,0] op_sel_hi:[1,1,1]
	v_pk_fma_f32 v[20:21], v[160:161], v[56:57], v[20:21] op_sel:[1,0,0] op_sel_hi:[1,1,1]
	v_pk_fma_f32 v[22:23], v[160:161], v[64:65], v[22:23] op_sel:[1,0,0] op_sel_hi:[1,1,1]
	v_pk_fma_f32 v[24:25], v[160:161], v[72:73], v[24:25] op_sel:[1,0,0] op_sel_hi:[1,1,1]
	v_pk_fma_f32 v[26:27], v[160:161], v[80:81], v[26:27] op_sel:[1,0,0] op_sel_hi:[1,1,1]
	v_pk_fma_f32 v[28:29], v[160:161], v[88:89], v[28:29] op_sel:[1,0,0] op_sel_hi:[1,1,1]
	v_pk_fma_f32 v[30:31], v[160:161], v[96:97], v[30:31] op_sel:[1,0,0] op_sel_hi:[1,1,1]
	v_fmac_f32_e32 v0, v161, v101
	v_add_u32_e32 v98, s10, v5
	s_add_i32 s10, s10, 16
	ds_read_b128 v[34:37], v98
	ds_read_b128 v[38:41], v98 offset:4096
	ds_read_b128 v[42:45], v98 offset:8192
	ds_read_b128 v[46:49], v98 offset:12288
	ds_read_b128 v[50:53], v98 offset:16384
	ds_read_b128 v[54:57], v98 offset:20480
	ds_read_b128 v[58:61], v98 offset:24576
	ds_read_b128 v[62:65], v98 offset:28672
	ds_read_b128 v[66:69], v98 offset:32768
	ds_read_b128 v[70:73], v98 offset:36864
	ds_read_b128 v[74:77], v98 offset:40960
	ds_read_b128 v[78:81], v98 offset:45056
	ds_read_b128 v[82:85], v98 offset:49152
	ds_read_b128 v[86:89], v98 offset:53248
	ds_read_b128 v[90:93], v98 offset:57344
	ds_read_b128 v[94:97], v98 offset:61440
	v_add_u32_e32 v98, 0x10000, v98
	ds_read_b128 v[98:101], v98
	s_waitcnt lgkmcnt(14)
	v_mov_b32_e32 v110, v34
	v_mov_b32_e32 v111, v38
	v_mov_b32_e32 v112, v42
	s_waitcnt lgkmcnt(13)
	v_mov_b32_e32 v113, v46
	s_waitcnt lgkmcnt(12)
	v_mov_b32_e32 v114, v50
	s_waitcnt lgkmcnt(11)
	v_mov_b32_e32 v115, v54
	s_waitcnt lgkmcnt(10)
	v_mov_b32_e32 v116, v58
	s_waitcnt lgkmcnt(9)
	v_mov_b32_e32 v117, v62
	s_waitcnt lgkmcnt(8)
	v_mov_b32_e32 v118, v66
	s_waitcnt lgkmcnt(7)
	v_mov_b32_e32 v119, v70
	s_waitcnt lgkmcnt(6)
	v_mov_b32_e32 v120, v74
	s_waitcnt lgkmcnt(5)
	v_mov_b32_e32 v121, v78
	s_waitcnt lgkmcnt(4)
	v_mov_b32_e32 v122, v82
	s_waitcnt lgkmcnt(3)
	v_mov_b32_e32 v123, v86
	s_waitcnt lgkmcnt(2)
	v_mov_b32_e32 v124, v90
	s_waitcnt lgkmcnt(1)
	v_mov_b32_e32 v125, v94
	v_mov_b32_e32 v38, v35
	v_mov_b32_e32 v46, v43
	v_mov_b32_e32 v54, v51
	v_mov_b32_e32 v62, v59
	v_mov_b32_e32 v70, v67
	v_mov_b32_e32 v78, v75
	v_mov_b32_e32 v86, v83
	v_mov_b32_e32 v94, v91
	v_mov_b32_e32 v34, v36
	v_mov_b32_e32 v35, v40
	v_mov_b32_e32 v42, v44
	v_mov_b32_e32 v43, v48
	v_mov_b32_e32 v50, v52
	v_mov_b32_e32 v51, v56
	v_mov_b32_e32 v58, v60
	v_mov_b32_e32 v59, v64
	v_mov_b32_e32 v66, v68
	v_mov_b32_e32 v67, v72
	v_mov_b32_e32 v74, v76
	v_mov_b32_e32 v75, v80
	v_mov_b32_e32 v82, v84
	v_mov_b32_e32 v83, v88
	v_mov_b32_e32 v90, v92
	v_mov_b32_e32 v91, v96
	v_mov_b32_e32 v40, v37
	v_mov_b32_e32 v48, v45
	v_mov_b32_e32 v56, v53
	v_mov_b32_e32 v64, v61
	v_mov_b32_e32 v72, v69
	v_mov_b32_e32 v80, v77
	v_mov_b32_e32 v88, v85
	v_mov_b32_e32 v96, v93
	s_waitcnt vmcnt(27)
	v_pk_fma_f32 v[16:17], v[162:163], v[110:111], v[16:17] op_sel_hi:[0,1,1]
	v_pk_fma_f32 v[18:19], v[162:163], v[112:113], v[18:19] op_sel_hi:[0,1,1]
	v_pk_fma_f32 v[20:21], v[162:163], v[114:115], v[20:21] op_sel_hi:[0,1,1]
	v_pk_fma_f32 v[22:23], v[162:163], v[116:117], v[22:23] op_sel_hi:[0,1,1]
	v_pk_fma_f32 v[24:25], v[162:163], v[118:119], v[24:25] op_sel_hi:[0,1,1]
	v_pk_fma_f32 v[26:27], v[162:163], v[120:121], v[26:27] op_sel_hi:[0,1,1]
	v_pk_fma_f32 v[28:29], v[162:163], v[122:123], v[28:29] op_sel_hi:[0,1,1]
	v_pk_fma_f32 v[30:31], v[162:163], v[124:125], v[30:31] op_sel_hi:[0,1,1]
	s_waitcnt lgkmcnt(0)
	v_fmac_f32_e32 v0, v162, v98
	s_waitcnt vmcnt(26)
	v_pk_fma_f32 v[16:17], v[162:163], v[38:39], v[16:17] op_sel:[1,0,0] op_sel_hi:[1,1,1]
	v_pk_fma_f32 v[18:19], v[162:163], v[46:47], v[18:19] op_sel:[1,0,0] op_sel_hi:[1,1,1]
	v_pk_fma_f32 v[20:21], v[162:163], v[54:55], v[20:21] op_sel:[1,0,0] op_sel_hi:[1,1,1]
	v_pk_fma_f32 v[22:23], v[162:163], v[62:63], v[22:23] op_sel:[1,0,0] op_sel_hi:[1,1,1]
	v_pk_fma_f32 v[24:25], v[162:163], v[70:71], v[24:25] op_sel:[1,0,0] op_sel_hi:[1,1,1]
	v_pk_fma_f32 v[26:27], v[162:163], v[78:79], v[26:27] op_sel:[1,0,0] op_sel_hi:[1,1,1]
	v_pk_fma_f32 v[28:29], v[162:163], v[86:87], v[28:29] op_sel:[1,0,0] op_sel_hi:[1,1,1]
	v_pk_fma_f32 v[30:31], v[162:163], v[94:95], v[30:31] op_sel:[1,0,0] op_sel_hi:[1,1,1]
	v_fmac_f32_e32 v0, v163, v99
	s_waitcnt vmcnt(25)
	v_pk_fma_f32 v[16:17], v[164:165], v[34:35], v[16:17] op_sel_hi:[0,1,1]
	v_pk_fma_f32 v[18:19], v[164:165], v[42:43], v[18:19] op_sel_hi:[0,1,1]
	v_pk_fma_f32 v[20:21], v[164:165], v[50:51], v[20:21] op_sel_hi:[0,1,1]
	v_pk_fma_f32 v[22:23], v[164:165], v[58:59], v[22:23] op_sel_hi:[0,1,1]
	v_pk_fma_f32 v[24:25], v[164:165], v[66:67], v[24:25] op_sel_hi:[0,1,1]
	v_pk_fma_f32 v[26:27], v[164:165], v[74:75], v[26:27] op_sel_hi:[0,1,1]
	v_pk_fma_f32 v[28:29], v[164:165], v[82:83], v[28:29] op_sel_hi:[0,1,1]
	v_pk_fma_f32 v[30:31], v[164:165], v[90:91], v[30:31] op_sel_hi:[0,1,1]
	v_fmac_f32_e32 v0, v164, v100
	s_waitcnt vmcnt(24)
	v_pk_fma_f32 v[16:17], v[164:165], v[40:41], v[16:17] op_sel:[1,0,0] op_sel_hi:[1,1,1]
	v_pk_fma_f32 v[18:19], v[164:165], v[48:49], v[18:19] op_sel:[1,0,0] op_sel_hi:[1,1,1]
	v_pk_fma_f32 v[20:21], v[164:165], v[56:57], v[20:21] op_sel:[1,0,0] op_sel_hi:[1,1,1]
	v_pk_fma_f32 v[22:23], v[164:165], v[64:65], v[22:23] op_sel:[1,0,0] op_sel_hi:[1,1,1]
	v_pk_fma_f32 v[24:25], v[164:165], v[72:73], v[24:25] op_sel:[1,0,0] op_sel_hi:[1,1,1]
	v_pk_fma_f32 v[26:27], v[164:165], v[80:81], v[26:27] op_sel:[1,0,0] op_sel_hi:[1,1,1]
	v_pk_fma_f32 v[28:29], v[164:165], v[88:89], v[28:29] op_sel:[1,0,0] op_sel_hi:[1,1,1]
	v_pk_fma_f32 v[30:31], v[164:165], v[96:97], v[30:31] op_sel:[1,0,0] op_sel_hi:[1,1,1]
	v_fmac_f32_e32 v0, v165, v101
	v_add_u32_e32 v98, s10, v5
	s_add_i32 s10, s10, 16
	ds_read_b128 v[34:37], v98
	ds_read_b128 v[38:41], v98 offset:4096
	ds_read_b128 v[42:45], v98 offset:8192
	ds_read_b128 v[46:49], v98 offset:12288
	ds_read_b128 v[50:53], v98 offset:16384
	ds_read_b128 v[54:57], v98 offset:20480
	ds_read_b128 v[58:61], v98 offset:24576
	ds_read_b128 v[62:65], v98 offset:28672
	ds_read_b128 v[66:69], v98 offset:32768
	ds_read_b128 v[70:73], v98 offset:36864
	ds_read_b128 v[74:77], v98 offset:40960
	ds_read_b128 v[78:81], v98 offset:45056
	ds_read_b128 v[82:85], v98 offset:49152
	ds_read_b128 v[86:89], v98 offset:53248
	ds_read_b128 v[90:93], v98 offset:57344
	ds_read_b128 v[94:97], v98 offset:61440
	v_add_u32_e32 v98, 0x10000, v98
	ds_read_b128 v[98:101], v98
	s_waitcnt lgkmcnt(14)
	v_mov_b32_e32 v110, v34
	v_mov_b32_e32 v111, v38
	v_mov_b32_e32 v112, v42
	s_waitcnt lgkmcnt(13)
	v_mov_b32_e32 v113, v46
	s_waitcnt lgkmcnt(12)
	v_mov_b32_e32 v114, v50
	s_waitcnt lgkmcnt(11)
	v_mov_b32_e32 v115, v54
	s_waitcnt lgkmcnt(10)
	v_mov_b32_e32 v116, v58
	s_waitcnt lgkmcnt(9)
	v_mov_b32_e32 v117, v62
	s_waitcnt lgkmcnt(8)
	v_mov_b32_e32 v118, v66
	s_waitcnt lgkmcnt(7)
	v_mov_b32_e32 v119, v70
	s_waitcnt lgkmcnt(6)
	v_mov_b32_e32 v120, v74
	s_waitcnt lgkmcnt(5)
	v_mov_b32_e32 v121, v78
	s_waitcnt lgkmcnt(4)
	v_mov_b32_e32 v122, v82
	s_waitcnt lgkmcnt(3)
	v_mov_b32_e32 v123, v86
	s_waitcnt lgkmcnt(2)
	v_mov_b32_e32 v124, v90
	s_waitcnt lgkmcnt(1)
	v_mov_b32_e32 v125, v94
	v_mov_b32_e32 v38, v35
	v_mov_b32_e32 v46, v43
	v_mov_b32_e32 v54, v51
	v_mov_b32_e32 v62, v59
	v_mov_b32_e32 v70, v67
	v_mov_b32_e32 v78, v75
	v_mov_b32_e32 v86, v83
	v_mov_b32_e32 v94, v91
	v_mov_b32_e32 v34, v36
	v_mov_b32_e32 v35, v40
	v_mov_b32_e32 v42, v44
	v_mov_b32_e32 v43, v48
	v_mov_b32_e32 v50, v52
	v_mov_b32_e32 v51, v56
	v_mov_b32_e32 v58, v60
	v_mov_b32_e32 v59, v64
	v_mov_b32_e32 v66, v68
	v_mov_b32_e32 v67, v72
	v_mov_b32_e32 v74, v76
	v_mov_b32_e32 v75, v80
	v_mov_b32_e32 v82, v84
	v_mov_b32_e32 v83, v88
	v_mov_b32_e32 v90, v92
	v_mov_b32_e32 v91, v96
	v_mov_b32_e32 v40, v37
	v_mov_b32_e32 v48, v45
	v_mov_b32_e32 v56, v53
	v_mov_b32_e32 v64, v61
	v_mov_b32_e32 v72, v69
	v_mov_b32_e32 v80, v77
	v_mov_b32_e32 v88, v85
	v_mov_b32_e32 v96, v93
	s_waitcnt vmcnt(23)
	v_pk_fma_f32 v[16:17], v[166:167], v[110:111], v[16:17] op_sel_hi:[0,1,1]
	v_pk_fma_f32 v[18:19], v[166:167], v[112:113], v[18:19] op_sel_hi:[0,1,1]
	v_pk_fma_f32 v[20:21], v[166:167], v[114:115], v[20:21] op_sel_hi:[0,1,1]
	v_pk_fma_f32 v[22:23], v[166:167], v[116:117], v[22:23] op_sel_hi:[0,1,1]
	v_pk_fma_f32 v[24:25], v[166:167], v[118:119], v[24:25] op_sel_hi:[0,1,1]
	v_pk_fma_f32 v[26:27], v[166:167], v[120:121], v[26:27] op_sel_hi:[0,1,1]
	v_pk_fma_f32 v[28:29], v[166:167], v[122:123], v[28:29] op_sel_hi:[0,1,1]
	v_pk_fma_f32 v[30:31], v[166:167], v[124:125], v[30:31] op_sel_hi:[0,1,1]
	s_waitcnt lgkmcnt(0)
	v_fmac_f32_e32 v0, v166, v98
	s_waitcnt vmcnt(22)
	v_pk_fma_f32 v[16:17], v[166:167], v[38:39], v[16:17] op_sel:[1,0,0] op_sel_hi:[1,1,1]
	v_pk_fma_f32 v[18:19], v[166:167], v[46:47], v[18:19] op_sel:[1,0,0] op_sel_hi:[1,1,1]
	v_pk_fma_f32 v[20:21], v[166:167], v[54:55], v[20:21] op_sel:[1,0,0] op_sel_hi:[1,1,1]
	v_pk_fma_f32 v[22:23], v[166:167], v[62:63], v[22:23] op_sel:[1,0,0] op_sel_hi:[1,1,1]
	v_pk_fma_f32 v[24:25], v[166:167], v[70:71], v[24:25] op_sel:[1,0,0] op_sel_hi:[1,1,1]
	v_pk_fma_f32 v[26:27], v[166:167], v[78:79], v[26:27] op_sel:[1,0,0] op_sel_hi:[1,1,1]
	v_pk_fma_f32 v[28:29], v[166:167], v[86:87], v[28:29] op_sel:[1,0,0] op_sel_hi:[1,1,1]
	v_pk_fma_f32 v[30:31], v[166:167], v[94:95], v[30:31] op_sel:[1,0,0] op_sel_hi:[1,1,1]
	v_fmac_f32_e32 v0, v167, v99
	s_waitcnt vmcnt(21)
	v_pk_fma_f32 v[16:17], v[168:169], v[34:35], v[16:17] op_sel_hi:[0,1,1]
	v_pk_fma_f32 v[18:19], v[168:169], v[42:43], v[18:19] op_sel_hi:[0,1,1]
	v_pk_fma_f32 v[20:21], v[168:169], v[50:51], v[20:21] op_sel_hi:[0,1,1]
	v_pk_fma_f32 v[22:23], v[168:169], v[58:59], v[22:23] op_sel_hi:[0,1,1]
	v_pk_fma_f32 v[24:25], v[168:169], v[66:67], v[24:25] op_sel_hi:[0,1,1]
	v_pk_fma_f32 v[26:27], v[168:169], v[74:75], v[26:27] op_sel_hi:[0,1,1]
	v_pk_fma_f32 v[28:29], v[168:169], v[82:83], v[28:29] op_sel_hi:[0,1,1]
	v_pk_fma_f32 v[30:31], v[168:169], v[90:91], v[30:31] op_sel_hi:[0,1,1]
	v_fmac_f32_e32 v0, v168, v100
	s_waitcnt vmcnt(20)
	v_pk_fma_f32 v[16:17], v[168:169], v[40:41], v[16:17] op_sel:[1,0,0] op_sel_hi:[1,1,1]
	v_pk_fma_f32 v[18:19], v[168:169], v[48:49], v[18:19] op_sel:[1,0,0] op_sel_hi:[1,1,1]
	v_pk_fma_f32 v[20:21], v[168:169], v[56:57], v[20:21] op_sel:[1,0,0] op_sel_hi:[1,1,1]
	v_pk_fma_f32 v[22:23], v[168:169], v[64:65], v[22:23] op_sel:[1,0,0] op_sel_hi:[1,1,1]
	v_pk_fma_f32 v[24:25], v[168:169], v[72:73], v[24:25] op_sel:[1,0,0] op_sel_hi:[1,1,1]
	v_pk_fma_f32 v[26:27], v[168:169], v[80:81], v[26:27] op_sel:[1,0,0] op_sel_hi:[1,1,1]
	v_pk_fma_f32 v[28:29], v[168:169], v[88:89], v[28:29] op_sel:[1,0,0] op_sel_hi:[1,1,1]
	v_pk_fma_f32 v[30:31], v[168:169], v[96:97], v[30:31] op_sel:[1,0,0] op_sel_hi:[1,1,1]
	v_fmac_f32_e32 v0, v169, v101
	v_add_u32_e32 v98, s10, v5
	s_add_i32 s10, s10, 16
	ds_read_b128 v[34:37], v98
	ds_read_b128 v[38:41], v98 offset:4096
	ds_read_b128 v[42:45], v98 offset:8192
	ds_read_b128 v[46:49], v98 offset:12288
	ds_read_b128 v[50:53], v98 offset:16384
	ds_read_b128 v[54:57], v98 offset:20480
	ds_read_b128 v[58:61], v98 offset:24576
	ds_read_b128 v[62:65], v98 offset:28672
	ds_read_b128 v[66:69], v98 offset:32768
	ds_read_b128 v[70:73], v98 offset:36864
	ds_read_b128 v[74:77], v98 offset:40960
	ds_read_b128 v[78:81], v98 offset:45056
	ds_read_b128 v[82:85], v98 offset:49152
	ds_read_b128 v[86:89], v98 offset:53248
	ds_read_b128 v[90:93], v98 offset:57344
	ds_read_b128 v[94:97], v98 offset:61440
	v_add_u32_e32 v98, 0x10000, v98
	ds_read_b128 v[98:101], v98
	s_waitcnt lgkmcnt(14)
	v_mov_b32_e32 v110, v34
	v_mov_b32_e32 v111, v38
	v_mov_b32_e32 v112, v42
	s_waitcnt lgkmcnt(13)
	v_mov_b32_e32 v113, v46
	s_waitcnt lgkmcnt(12)
	v_mov_b32_e32 v114, v50
	s_waitcnt lgkmcnt(11)
	v_mov_b32_e32 v115, v54
	s_waitcnt lgkmcnt(10)
	v_mov_b32_e32 v116, v58
	s_waitcnt lgkmcnt(9)
	v_mov_b32_e32 v117, v62
	s_waitcnt lgkmcnt(8)
	v_mov_b32_e32 v118, v66
	s_waitcnt lgkmcnt(7)
	v_mov_b32_e32 v119, v70
	s_waitcnt lgkmcnt(6)
	v_mov_b32_e32 v120, v74
	s_waitcnt lgkmcnt(5)
	v_mov_b32_e32 v121, v78
	s_waitcnt lgkmcnt(4)
	v_mov_b32_e32 v122, v82
	s_waitcnt lgkmcnt(3)
	v_mov_b32_e32 v123, v86
	s_waitcnt lgkmcnt(2)
	v_mov_b32_e32 v124, v90
	s_waitcnt lgkmcnt(1)
	v_mov_b32_e32 v125, v94
	v_mov_b32_e32 v38, v35
	v_mov_b32_e32 v46, v43
	v_mov_b32_e32 v54, v51
	v_mov_b32_e32 v62, v59
	v_mov_b32_e32 v70, v67
	v_mov_b32_e32 v78, v75
	v_mov_b32_e32 v86, v83
	v_mov_b32_e32 v94, v91
	v_mov_b32_e32 v34, v36
	v_mov_b32_e32 v35, v40
	v_mov_b32_e32 v42, v44
	v_mov_b32_e32 v43, v48
	v_mov_b32_e32 v50, v52
	v_mov_b32_e32 v51, v56
	v_mov_b32_e32 v58, v60
	v_mov_b32_e32 v59, v64
	v_mov_b32_e32 v66, v68
	v_mov_b32_e32 v67, v72
	v_mov_b32_e32 v74, v76
	v_mov_b32_e32 v75, v80
	v_mov_b32_e32 v82, v84
	v_mov_b32_e32 v83, v88
	v_mov_b32_e32 v90, v92
	v_mov_b32_e32 v91, v96
	v_mov_b32_e32 v40, v37
	v_mov_b32_e32 v48, v45
	v_mov_b32_e32 v56, v53
	v_mov_b32_e32 v64, v61
	v_mov_b32_e32 v72, v69
	v_mov_b32_e32 v80, v77
	v_mov_b32_e32 v88, v85
	v_mov_b32_e32 v96, v93
	s_waitcnt vmcnt(19)
	v_pk_fma_f32 v[16:17], v[170:171], v[110:111], v[16:17] op_sel_hi:[0,1,1]
	v_pk_fma_f32 v[18:19], v[170:171], v[112:113], v[18:19] op_sel_hi:[0,1,1]
	v_pk_fma_f32 v[20:21], v[170:171], v[114:115], v[20:21] op_sel_hi:[0,1,1]
	v_pk_fma_f32 v[22:23], v[170:171], v[116:117], v[22:23] op_sel_hi:[0,1,1]
	v_pk_fma_f32 v[24:25], v[170:171], v[118:119], v[24:25] op_sel_hi:[0,1,1]
	v_pk_fma_f32 v[26:27], v[170:171], v[120:121], v[26:27] op_sel_hi:[0,1,1]
	v_pk_fma_f32 v[28:29], v[170:171], v[122:123], v[28:29] op_sel_hi:[0,1,1]
	v_pk_fma_f32 v[30:31], v[170:171], v[124:125], v[30:31] op_sel_hi:[0,1,1]
	s_waitcnt lgkmcnt(0)
	v_fmac_f32_e32 v0, v170, v98
	s_waitcnt vmcnt(18)
	v_pk_fma_f32 v[16:17], v[170:171], v[38:39], v[16:17] op_sel:[1,0,0] op_sel_hi:[1,1,1]
	v_pk_fma_f32 v[18:19], v[170:171], v[46:47], v[18:19] op_sel:[1,0,0] op_sel_hi:[1,1,1]
	v_pk_fma_f32 v[20:21], v[170:171], v[54:55], v[20:21] op_sel:[1,0,0] op_sel_hi:[1,1,1]
	v_pk_fma_f32 v[22:23], v[170:171], v[62:63], v[22:23] op_sel:[1,0,0] op_sel_hi:[1,1,1]
	v_pk_fma_f32 v[24:25], v[170:171], v[70:71], v[24:25] op_sel:[1,0,0] op_sel_hi:[1,1,1]
	v_pk_fma_f32 v[26:27], v[170:171], v[78:79], v[26:27] op_sel:[1,0,0] op_sel_hi:[1,1,1]
	v_pk_fma_f32 v[28:29], v[170:171], v[86:87], v[28:29] op_sel:[1,0,0] op_sel_hi:[1,1,1]
	v_pk_fma_f32 v[30:31], v[170:171], v[94:95], v[30:31] op_sel:[1,0,0] op_sel_hi:[1,1,1]
	v_fmac_f32_e32 v0, v171, v99
	s_waitcnt vmcnt(17)
	v_pk_fma_f32 v[16:17], v[172:173], v[34:35], v[16:17] op_sel_hi:[0,1,1]
	v_pk_fma_f32 v[18:19], v[172:173], v[42:43], v[18:19] op_sel_hi:[0,1,1]
	v_pk_fma_f32 v[20:21], v[172:173], v[50:51], v[20:21] op_sel_hi:[0,1,1]
	v_pk_fma_f32 v[22:23], v[172:173], v[58:59], v[22:23] op_sel_hi:[0,1,1]
	v_pk_fma_f32 v[24:25], v[172:173], v[66:67], v[24:25] op_sel_hi:[0,1,1]
	v_pk_fma_f32 v[26:27], v[172:173], v[74:75], v[26:27] op_sel_hi:[0,1,1]
	v_pk_fma_f32 v[28:29], v[172:173], v[82:83], v[28:29] op_sel_hi:[0,1,1]
	v_pk_fma_f32 v[30:31], v[172:173], v[90:91], v[30:31] op_sel_hi:[0,1,1]
	v_fmac_f32_e32 v0, v172, v100
	s_waitcnt vmcnt(16)
	v_pk_fma_f32 v[16:17], v[172:173], v[40:41], v[16:17] op_sel:[1,0,0] op_sel_hi:[1,1,1]
	v_pk_fma_f32 v[18:19], v[172:173], v[48:49], v[18:19] op_sel:[1,0,0] op_sel_hi:[1,1,1]
	v_pk_fma_f32 v[20:21], v[172:173], v[56:57], v[20:21] op_sel:[1,0,0] op_sel_hi:[1,1,1]
	v_pk_fma_f32 v[22:23], v[172:173], v[64:65], v[22:23] op_sel:[1,0,0] op_sel_hi:[1,1,1]
	v_pk_fma_f32 v[24:25], v[172:173], v[72:73], v[24:25] op_sel:[1,0,0] op_sel_hi:[1,1,1]
	v_pk_fma_f32 v[26:27], v[172:173], v[80:81], v[26:27] op_sel:[1,0,0] op_sel_hi:[1,1,1]
	v_pk_fma_f32 v[28:29], v[172:173], v[88:89], v[28:29] op_sel:[1,0,0] op_sel_hi:[1,1,1]
	v_pk_fma_f32 v[30:31], v[172:173], v[96:97], v[30:31] op_sel:[1,0,0] op_sel_hi:[1,1,1]
	v_fmac_f32_e32 v0, v173, v101
	v_add_u32_e32 v98, s10, v5
	s_add_i32 s10, s10, 16
	ds_read_b128 v[34:37], v98
	ds_read_b128 v[38:41], v98 offset:4096
	ds_read_b128 v[42:45], v98 offset:8192
	ds_read_b128 v[46:49], v98 offset:12288
	ds_read_b128 v[50:53], v98 offset:16384
	ds_read_b128 v[54:57], v98 offset:20480
	ds_read_b128 v[58:61], v98 offset:24576
	ds_read_b128 v[62:65], v98 offset:28672
	ds_read_b128 v[66:69], v98 offset:32768
	ds_read_b128 v[70:73], v98 offset:36864
	ds_read_b128 v[74:77], v98 offset:40960
	ds_read_b128 v[78:81], v98 offset:45056
	ds_read_b128 v[82:85], v98 offset:49152
	ds_read_b128 v[86:89], v98 offset:53248
	ds_read_b128 v[90:93], v98 offset:57344
	ds_read_b128 v[94:97], v98 offset:61440
	v_add_u32_e32 v98, 0x10000, v98
	ds_read_b128 v[98:101], v98
	s_waitcnt lgkmcnt(14)
	v_mov_b32_e32 v110, v34
	v_mov_b32_e32 v111, v38
	v_mov_b32_e32 v112, v42
	s_waitcnt lgkmcnt(13)
	v_mov_b32_e32 v113, v46
	s_waitcnt lgkmcnt(12)
	v_mov_b32_e32 v114, v50
	s_waitcnt lgkmcnt(11)
	v_mov_b32_e32 v115, v54
	s_waitcnt lgkmcnt(10)
	v_mov_b32_e32 v116, v58
	s_waitcnt lgkmcnt(9)
	v_mov_b32_e32 v117, v62
	s_waitcnt lgkmcnt(8)
	v_mov_b32_e32 v118, v66
	s_waitcnt lgkmcnt(7)
	v_mov_b32_e32 v119, v70
	s_waitcnt lgkmcnt(6)
	v_mov_b32_e32 v120, v74
	s_waitcnt lgkmcnt(5)
	v_mov_b32_e32 v121, v78
	s_waitcnt lgkmcnt(4)
	v_mov_b32_e32 v122, v82
	s_waitcnt lgkmcnt(3)
	v_mov_b32_e32 v123, v86
	s_waitcnt lgkmcnt(2)
	v_mov_b32_e32 v124, v90
	s_waitcnt lgkmcnt(1)
	v_mov_b32_e32 v125, v94
	v_mov_b32_e32 v38, v35
	v_mov_b32_e32 v46, v43
	v_mov_b32_e32 v54, v51
	v_mov_b32_e32 v62, v59
	v_mov_b32_e32 v70, v67
	v_mov_b32_e32 v78, v75
	v_mov_b32_e32 v86, v83
	v_mov_b32_e32 v94, v91
	v_mov_b32_e32 v34, v36
	v_mov_b32_e32 v35, v40
	v_mov_b32_e32 v42, v44
	v_mov_b32_e32 v43, v48
	v_mov_b32_e32 v50, v52
	v_mov_b32_e32 v51, v56
	v_mov_b32_e32 v58, v60
	v_mov_b32_e32 v59, v64
	v_mov_b32_e32 v66, v68
	v_mov_b32_e32 v67, v72
	v_mov_b32_e32 v74, v76
	v_mov_b32_e32 v75, v80
	v_mov_b32_e32 v82, v84
	v_mov_b32_e32 v83, v88
	v_mov_b32_e32 v90, v92
	v_mov_b32_e32 v91, v96
	v_mov_b32_e32 v40, v37
	v_mov_b32_e32 v48, v45
	v_mov_b32_e32 v56, v53
	v_mov_b32_e32 v64, v61
	v_mov_b32_e32 v72, v69
	v_mov_b32_e32 v80, v77
	v_mov_b32_e32 v88, v85
	v_mov_b32_e32 v96, v93
	s_waitcnt vmcnt(15)
	v_pk_fma_f32 v[16:17], v[174:175], v[110:111], v[16:17] op_sel_hi:[0,1,1]
	v_pk_fma_f32 v[18:19], v[174:175], v[112:113], v[18:19] op_sel_hi:[0,1,1]
	v_pk_fma_f32 v[20:21], v[174:175], v[114:115], v[20:21] op_sel_hi:[0,1,1]
	v_pk_fma_f32 v[22:23], v[174:175], v[116:117], v[22:23] op_sel_hi:[0,1,1]
	v_pk_fma_f32 v[24:25], v[174:175], v[118:119], v[24:25] op_sel_hi:[0,1,1]
	v_pk_fma_f32 v[26:27], v[174:175], v[120:121], v[26:27] op_sel_hi:[0,1,1]
	v_pk_fma_f32 v[28:29], v[174:175], v[122:123], v[28:29] op_sel_hi:[0,1,1]
	v_pk_fma_f32 v[30:31], v[174:175], v[124:125], v[30:31] op_sel_hi:[0,1,1]
	s_waitcnt lgkmcnt(0)
	v_fmac_f32_e32 v0, v174, v98
	s_waitcnt vmcnt(14)
	v_pk_fma_f32 v[16:17], v[174:175], v[38:39], v[16:17] op_sel:[1,0,0] op_sel_hi:[1,1,1]
	v_pk_fma_f32 v[18:19], v[174:175], v[46:47], v[18:19] op_sel:[1,0,0] op_sel_hi:[1,1,1]
	v_pk_fma_f32 v[20:21], v[174:175], v[54:55], v[20:21] op_sel:[1,0,0] op_sel_hi:[1,1,1]
	v_pk_fma_f32 v[22:23], v[174:175], v[62:63], v[22:23] op_sel:[1,0,0] op_sel_hi:[1,1,1]
	v_pk_fma_f32 v[24:25], v[174:175], v[70:71], v[24:25] op_sel:[1,0,0] op_sel_hi:[1,1,1]
	v_pk_fma_f32 v[26:27], v[174:175], v[78:79], v[26:27] op_sel:[1,0,0] op_sel_hi:[1,1,1]
	v_pk_fma_f32 v[28:29], v[174:175], v[86:87], v[28:29] op_sel:[1,0,0] op_sel_hi:[1,1,1]
	v_pk_fma_f32 v[30:31], v[174:175], v[94:95], v[30:31] op_sel:[1,0,0] op_sel_hi:[1,1,1]
	v_fmac_f32_e32 v0, v175, v99
	s_waitcnt vmcnt(13)
	v_pk_fma_f32 v[16:17], v[176:177], v[34:35], v[16:17] op_sel_hi:[0,1,1]
	v_pk_fma_f32 v[18:19], v[176:177], v[42:43], v[18:19] op_sel_hi:[0,1,1]
	v_pk_fma_f32 v[20:21], v[176:177], v[50:51], v[20:21] op_sel_hi:[0,1,1]
	v_pk_fma_f32 v[22:23], v[176:177], v[58:59], v[22:23] op_sel_hi:[0,1,1]
	v_pk_fma_f32 v[24:25], v[176:177], v[66:67], v[24:25] op_sel_hi:[0,1,1]
	v_pk_fma_f32 v[26:27], v[176:177], v[74:75], v[26:27] op_sel_hi:[0,1,1]
	v_pk_fma_f32 v[28:29], v[176:177], v[82:83], v[28:29] op_sel_hi:[0,1,1]
	v_pk_fma_f32 v[30:31], v[176:177], v[90:91], v[30:31] op_sel_hi:[0,1,1]
	v_fmac_f32_e32 v0, v176, v100
	s_waitcnt vmcnt(12)
	v_pk_fma_f32 v[16:17], v[176:177], v[40:41], v[16:17] op_sel:[1,0,0] op_sel_hi:[1,1,1]
	v_pk_fma_f32 v[18:19], v[176:177], v[48:49], v[18:19] op_sel:[1,0,0] op_sel_hi:[1,1,1]
	v_pk_fma_f32 v[20:21], v[176:177], v[56:57], v[20:21] op_sel:[1,0,0] op_sel_hi:[1,1,1]
	v_pk_fma_f32 v[22:23], v[176:177], v[64:65], v[22:23] op_sel:[1,0,0] op_sel_hi:[1,1,1]
	v_pk_fma_f32 v[24:25], v[176:177], v[72:73], v[24:25] op_sel:[1,0,0] op_sel_hi:[1,1,1]
	v_pk_fma_f32 v[26:27], v[176:177], v[80:81], v[26:27] op_sel:[1,0,0] op_sel_hi:[1,1,1]
	v_pk_fma_f32 v[28:29], v[176:177], v[88:89], v[28:29] op_sel:[1,0,0] op_sel_hi:[1,1,1]
	v_pk_fma_f32 v[30:31], v[176:177], v[96:97], v[30:31] op_sel:[1,0,0] op_sel_hi:[1,1,1]
	v_fmac_f32_e32 v0, v177, v101
	v_add_u32_e32 v98, s10, v5
	s_add_i32 s10, s10, 16
	ds_read_b128 v[34:37], v98
	ds_read_b128 v[38:41], v98 offset:4096
	ds_read_b128 v[42:45], v98 offset:8192
	ds_read_b128 v[46:49], v98 offset:12288
	ds_read_b128 v[50:53], v98 offset:16384
	ds_read_b128 v[54:57], v98 offset:20480
	ds_read_b128 v[58:61], v98 offset:24576
	ds_read_b128 v[62:65], v98 offset:28672
	ds_read_b128 v[66:69], v98 offset:32768
	ds_read_b128 v[70:73], v98 offset:36864
	ds_read_b128 v[74:77], v98 offset:40960
	ds_read_b128 v[78:81], v98 offset:45056
	ds_read_b128 v[82:85], v98 offset:49152
	ds_read_b128 v[86:89], v98 offset:53248
	ds_read_b128 v[90:93], v98 offset:57344
	ds_read_b128 v[94:97], v98 offset:61440
	v_add_u32_e32 v98, 0x10000, v98
	ds_read_b128 v[98:101], v98
	s_waitcnt lgkmcnt(14)
	v_mov_b32_e32 v110, v34
	v_mov_b32_e32 v111, v38
	v_mov_b32_e32 v112, v42
	s_waitcnt lgkmcnt(13)
	v_mov_b32_e32 v113, v46
	s_waitcnt lgkmcnt(12)
	v_mov_b32_e32 v114, v50
	s_waitcnt lgkmcnt(11)
	v_mov_b32_e32 v115, v54
	s_waitcnt lgkmcnt(10)
	v_mov_b32_e32 v116, v58
	s_waitcnt lgkmcnt(9)
	v_mov_b32_e32 v117, v62
	s_waitcnt lgkmcnt(8)
	v_mov_b32_e32 v118, v66
	s_waitcnt lgkmcnt(7)
	v_mov_b32_e32 v119, v70
	s_waitcnt lgkmcnt(6)
	v_mov_b32_e32 v120, v74
	s_waitcnt lgkmcnt(5)
	v_mov_b32_e32 v121, v78
	s_waitcnt lgkmcnt(4)
	v_mov_b32_e32 v122, v82
	s_waitcnt lgkmcnt(3)
	v_mov_b32_e32 v123, v86
	s_waitcnt lgkmcnt(2)
	v_mov_b32_e32 v124, v90
	s_waitcnt lgkmcnt(1)
	v_mov_b32_e32 v125, v94
	v_mov_b32_e32 v38, v35
	v_mov_b32_e32 v46, v43
	v_mov_b32_e32 v54, v51
	v_mov_b32_e32 v62, v59
	v_mov_b32_e32 v70, v67
	v_mov_b32_e32 v78, v75
	v_mov_b32_e32 v86, v83
	v_mov_b32_e32 v94, v91
	v_mov_b32_e32 v34, v36
	v_mov_b32_e32 v35, v40
	v_mov_b32_e32 v42, v44
	v_mov_b32_e32 v43, v48
	v_mov_b32_e32 v50, v52
	v_mov_b32_e32 v51, v56
	v_mov_b32_e32 v58, v60
	v_mov_b32_e32 v59, v64
	v_mov_b32_e32 v66, v68
	v_mov_b32_e32 v67, v72
	v_mov_b32_e32 v74, v76
	v_mov_b32_e32 v75, v80
	v_mov_b32_e32 v82, v84
	v_mov_b32_e32 v83, v88
	v_mov_b32_e32 v90, v92
	v_mov_b32_e32 v91, v96
	v_mov_b32_e32 v40, v37
	v_mov_b32_e32 v48, v45
	v_mov_b32_e32 v56, v53
	v_mov_b32_e32 v64, v61
	v_mov_b32_e32 v72, v69
	v_mov_b32_e32 v80, v77
	v_mov_b32_e32 v88, v85
	v_mov_b32_e32 v96, v93
	s_waitcnt vmcnt(11)
	v_pk_fma_f32 v[16:17], v[178:179], v[110:111], v[16:17] op_sel_hi:[0,1,1]
	v_pk_fma_f32 v[18:19], v[178:179], v[112:113], v[18:19] op_sel_hi:[0,1,1]
	v_pk_fma_f32 v[20:21], v[178:179], v[114:115], v[20:21] op_sel_hi:[0,1,1]
	v_pk_fma_f32 v[22:23], v[178:179], v[116:117], v[22:23] op_sel_hi:[0,1,1]
	v_pk_fma_f32 v[24:25], v[178:179], v[118:119], v[24:25] op_sel_hi:[0,1,1]
	v_pk_fma_f32 v[26:27], v[178:179], v[120:121], v[26:27] op_sel_hi:[0,1,1]
	v_pk_fma_f32 v[28:29], v[178:179], v[122:123], v[28:29] op_sel_hi:[0,1,1]
	v_pk_fma_f32 v[30:31], v[178:179], v[124:125], v[30:31] op_sel_hi:[0,1,1]
	s_waitcnt lgkmcnt(0)
	v_fmac_f32_e32 v0, v178, v98
	s_waitcnt vmcnt(10)
	v_pk_fma_f32 v[16:17], v[178:179], v[38:39], v[16:17] op_sel:[1,0,0] op_sel_hi:[1,1,1]
	v_pk_fma_f32 v[18:19], v[178:179], v[46:47], v[18:19] op_sel:[1,0,0] op_sel_hi:[1,1,1]
	v_pk_fma_f32 v[20:21], v[178:179], v[54:55], v[20:21] op_sel:[1,0,0] op_sel_hi:[1,1,1]
	v_pk_fma_f32 v[22:23], v[178:179], v[62:63], v[22:23] op_sel:[1,0,0] op_sel_hi:[1,1,1]
	v_pk_fma_f32 v[24:25], v[178:179], v[70:71], v[24:25] op_sel:[1,0,0] op_sel_hi:[1,1,1]
	v_pk_fma_f32 v[26:27], v[178:179], v[78:79], v[26:27] op_sel:[1,0,0] op_sel_hi:[1,1,1]
	v_pk_fma_f32 v[28:29], v[178:179], v[86:87], v[28:29] op_sel:[1,0,0] op_sel_hi:[1,1,1]
	v_pk_fma_f32 v[30:31], v[178:179], v[94:95], v[30:31] op_sel:[1,0,0] op_sel_hi:[1,1,1]
	v_fmac_f32_e32 v0, v179, v99
	s_waitcnt vmcnt(9)
	v_pk_fma_f32 v[16:17], v[180:181], v[34:35], v[16:17] op_sel_hi:[0,1,1]
	v_pk_fma_f32 v[18:19], v[180:181], v[42:43], v[18:19] op_sel_hi:[0,1,1]
	v_pk_fma_f32 v[20:21], v[180:181], v[50:51], v[20:21] op_sel_hi:[0,1,1]
	v_pk_fma_f32 v[22:23], v[180:181], v[58:59], v[22:23] op_sel_hi:[0,1,1]
	v_pk_fma_f32 v[24:25], v[180:181], v[66:67], v[24:25] op_sel_hi:[0,1,1]
	v_pk_fma_f32 v[26:27], v[180:181], v[74:75], v[26:27] op_sel_hi:[0,1,1]
	v_pk_fma_f32 v[28:29], v[180:181], v[82:83], v[28:29] op_sel_hi:[0,1,1]
	v_pk_fma_f32 v[30:31], v[180:181], v[90:91], v[30:31] op_sel_hi:[0,1,1]
	v_fmac_f32_e32 v0, v180, v100
	s_waitcnt vmcnt(8)
	v_pk_fma_f32 v[16:17], v[180:181], v[40:41], v[16:17] op_sel:[1,0,0] op_sel_hi:[1,1,1]
	v_pk_fma_f32 v[18:19], v[180:181], v[48:49], v[18:19] op_sel:[1,0,0] op_sel_hi:[1,1,1]
	v_pk_fma_f32 v[20:21], v[180:181], v[56:57], v[20:21] op_sel:[1,0,0] op_sel_hi:[1,1,1]
	v_pk_fma_f32 v[22:23], v[180:181], v[64:65], v[22:23] op_sel:[1,0,0] op_sel_hi:[1,1,1]
	v_pk_fma_f32 v[24:25], v[180:181], v[72:73], v[24:25] op_sel:[1,0,0] op_sel_hi:[1,1,1]
	v_pk_fma_f32 v[26:27], v[180:181], v[80:81], v[26:27] op_sel:[1,0,0] op_sel_hi:[1,1,1]
	v_pk_fma_f32 v[28:29], v[180:181], v[88:89], v[28:29] op_sel:[1,0,0] op_sel_hi:[1,1,1]
	v_pk_fma_f32 v[30:31], v[180:181], v[96:97], v[30:31] op_sel:[1,0,0] op_sel_hi:[1,1,1]
	v_fmac_f32_e32 v0, v181, v101
	v_add_u32_e32 v98, s10, v5
	s_add_i32 s10, s10, 16
	ds_read_b128 v[34:37], v98
	ds_read_b128 v[38:41], v98 offset:4096
	ds_read_b128 v[42:45], v98 offset:8192
	ds_read_b128 v[46:49], v98 offset:12288
	ds_read_b128 v[50:53], v98 offset:16384
	ds_read_b128 v[54:57], v98 offset:20480
	ds_read_b128 v[58:61], v98 offset:24576
	ds_read_b128 v[62:65], v98 offset:28672
	ds_read_b128 v[66:69], v98 offset:32768
	ds_read_b128 v[70:73], v98 offset:36864
	ds_read_b128 v[74:77], v98 offset:40960
	ds_read_b128 v[78:81], v98 offset:45056
	ds_read_b128 v[82:85], v98 offset:49152
	ds_read_b128 v[86:89], v98 offset:53248
	ds_read_b128 v[90:93], v98 offset:57344
	ds_read_b128 v[94:97], v98 offset:61440
	v_add_u32_e32 v98, 0x10000, v98
	ds_read_b128 v[98:101], v98
	s_waitcnt lgkmcnt(14)
	v_mov_b32_e32 v110, v34
	v_mov_b32_e32 v111, v38
	v_mov_b32_e32 v112, v42
	s_waitcnt lgkmcnt(13)
	v_mov_b32_e32 v113, v46
	s_waitcnt lgkmcnt(12)
	v_mov_b32_e32 v114, v50
	s_waitcnt lgkmcnt(11)
	v_mov_b32_e32 v115, v54
	s_waitcnt lgkmcnt(10)
	v_mov_b32_e32 v116, v58
	s_waitcnt lgkmcnt(9)
	v_mov_b32_e32 v117, v62
	s_waitcnt lgkmcnt(8)
	v_mov_b32_e32 v118, v66
	s_waitcnt lgkmcnt(7)
	v_mov_b32_e32 v119, v70
	s_waitcnt lgkmcnt(6)
	v_mov_b32_e32 v120, v74
	s_waitcnt lgkmcnt(5)
	v_mov_b32_e32 v121, v78
	s_waitcnt lgkmcnt(4)
	v_mov_b32_e32 v122, v82
	s_waitcnt lgkmcnt(3)
	v_mov_b32_e32 v123, v86
	s_waitcnt lgkmcnt(2)
	v_mov_b32_e32 v124, v90
	s_waitcnt lgkmcnt(1)
	v_mov_b32_e32 v125, v94
	v_mov_b32_e32 v38, v35
	v_mov_b32_e32 v46, v43
	v_mov_b32_e32 v54, v51
	v_mov_b32_e32 v62, v59
	v_mov_b32_e32 v70, v67
	v_mov_b32_e32 v78, v75
	v_mov_b32_e32 v86, v83
	v_mov_b32_e32 v94, v91
	v_mov_b32_e32 v34, v36
	v_mov_b32_e32 v35, v40
	v_mov_b32_e32 v42, v44
	v_mov_b32_e32 v43, v48
	v_mov_b32_e32 v50, v52
	v_mov_b32_e32 v51, v56
	v_mov_b32_e32 v58, v60
	v_mov_b32_e32 v59, v64
	v_mov_b32_e32 v66, v68
	v_mov_b32_e32 v67, v72
	v_mov_b32_e32 v74, v76
	v_mov_b32_e32 v75, v80
	v_mov_b32_e32 v82, v84
	v_mov_b32_e32 v83, v88
	v_mov_b32_e32 v90, v92
	v_mov_b32_e32 v91, v96
	v_mov_b32_e32 v40, v37
	v_mov_b32_e32 v48, v45
	v_mov_b32_e32 v56, v53
	v_mov_b32_e32 v64, v61
	v_mov_b32_e32 v72, v69
	v_mov_b32_e32 v80, v77
	v_mov_b32_e32 v88, v85
	v_mov_b32_e32 v96, v93
	s_waitcnt vmcnt(7)
	v_pk_fma_f32 v[16:17], v[182:183], v[110:111], v[16:17] op_sel_hi:[0,1,1]
	v_pk_fma_f32 v[18:19], v[182:183], v[112:113], v[18:19] op_sel_hi:[0,1,1]
	v_pk_fma_f32 v[20:21], v[182:183], v[114:115], v[20:21] op_sel_hi:[0,1,1]
	v_pk_fma_f32 v[22:23], v[182:183], v[116:117], v[22:23] op_sel_hi:[0,1,1]
	v_pk_fma_f32 v[24:25], v[182:183], v[118:119], v[24:25] op_sel_hi:[0,1,1]
	v_pk_fma_f32 v[26:27], v[182:183], v[120:121], v[26:27] op_sel_hi:[0,1,1]
	v_pk_fma_f32 v[28:29], v[182:183], v[122:123], v[28:29] op_sel_hi:[0,1,1]
	v_pk_fma_f32 v[30:31], v[182:183], v[124:125], v[30:31] op_sel_hi:[0,1,1]
	s_waitcnt lgkmcnt(0)
	v_fmac_f32_e32 v0, v182, v98
	s_waitcnt vmcnt(6)
	v_pk_fma_f32 v[16:17], v[182:183], v[38:39], v[16:17] op_sel:[1,0,0] op_sel_hi:[1,1,1]
	v_pk_fma_f32 v[18:19], v[182:183], v[46:47], v[18:19] op_sel:[1,0,0] op_sel_hi:[1,1,1]
	v_pk_fma_f32 v[20:21], v[182:183], v[54:55], v[20:21] op_sel:[1,0,0] op_sel_hi:[1,1,1]
	v_pk_fma_f32 v[22:23], v[182:183], v[62:63], v[22:23] op_sel:[1,0,0] op_sel_hi:[1,1,1]
	v_pk_fma_f32 v[24:25], v[182:183], v[70:71], v[24:25] op_sel:[1,0,0] op_sel_hi:[1,1,1]
	v_pk_fma_f32 v[26:27], v[182:183], v[78:79], v[26:27] op_sel:[1,0,0] op_sel_hi:[1,1,1]
	v_pk_fma_f32 v[28:29], v[182:183], v[86:87], v[28:29] op_sel:[1,0,0] op_sel_hi:[1,1,1]
	v_pk_fma_f32 v[30:31], v[182:183], v[94:95], v[30:31] op_sel:[1,0,0] op_sel_hi:[1,1,1]
	v_fmac_f32_e32 v0, v183, v99
	s_waitcnt vmcnt(5)
	v_pk_fma_f32 v[16:17], v[184:185], v[34:35], v[16:17] op_sel_hi:[0,1,1]
	v_pk_fma_f32 v[18:19], v[184:185], v[42:43], v[18:19] op_sel_hi:[0,1,1]
	v_pk_fma_f32 v[20:21], v[184:185], v[50:51], v[20:21] op_sel_hi:[0,1,1]
	v_pk_fma_f32 v[22:23], v[184:185], v[58:59], v[22:23] op_sel_hi:[0,1,1]
	v_pk_fma_f32 v[24:25], v[184:185], v[66:67], v[24:25] op_sel_hi:[0,1,1]
	v_pk_fma_f32 v[26:27], v[184:185], v[74:75], v[26:27] op_sel_hi:[0,1,1]
	v_pk_fma_f32 v[28:29], v[184:185], v[82:83], v[28:29] op_sel_hi:[0,1,1]
	v_pk_fma_f32 v[30:31], v[184:185], v[90:91], v[30:31] op_sel_hi:[0,1,1]
	v_fmac_f32_e32 v0, v184, v100
	s_waitcnt vmcnt(4)
	v_pk_fma_f32 v[16:17], v[184:185], v[40:41], v[16:17] op_sel:[1,0,0] op_sel_hi:[1,1,1]
	v_pk_fma_f32 v[18:19], v[184:185], v[48:49], v[18:19] op_sel:[1,0,0] op_sel_hi:[1,1,1]
	v_pk_fma_f32 v[20:21], v[184:185], v[56:57], v[20:21] op_sel:[1,0,0] op_sel_hi:[1,1,1]
	v_pk_fma_f32 v[22:23], v[184:185], v[64:65], v[22:23] op_sel:[1,0,0] op_sel_hi:[1,1,1]
	v_pk_fma_f32 v[24:25], v[184:185], v[72:73], v[24:25] op_sel:[1,0,0] op_sel_hi:[1,1,1]
	v_pk_fma_f32 v[26:27], v[184:185], v[80:81], v[26:27] op_sel:[1,0,0] op_sel_hi:[1,1,1]
	v_pk_fma_f32 v[28:29], v[184:185], v[88:89], v[28:29] op_sel:[1,0,0] op_sel_hi:[1,1,1]
	v_pk_fma_f32 v[30:31], v[184:185], v[96:97], v[30:31] op_sel:[1,0,0] op_sel_hi:[1,1,1]
	v_fmac_f32_e32 v0, v185, v101
	v_add_u32_e32 v98, s10, v5
	s_add_i32 s10, s10, 16
	ds_read_b128 v[34:37], v98
	ds_read_b128 v[38:41], v98 offset:4096
	ds_read_b128 v[42:45], v98 offset:8192
	ds_read_b128 v[46:49], v98 offset:12288
	ds_read_b128 v[50:53], v98 offset:16384
	ds_read_b128 v[54:57], v98 offset:20480
	ds_read_b128 v[58:61], v98 offset:24576
	ds_read_b128 v[62:65], v98 offset:28672
	ds_read_b128 v[66:69], v98 offset:32768
	ds_read_b128 v[70:73], v98 offset:36864
	ds_read_b128 v[74:77], v98 offset:40960
	ds_read_b128 v[78:81], v98 offset:45056
	ds_read_b128 v[82:85], v98 offset:49152
	ds_read_b128 v[86:89], v98 offset:53248
	ds_read_b128 v[90:93], v98 offset:57344
	ds_read_b128 v[94:97], v98 offset:61440
	v_add_u32_e32 v98, 0x10000, v98
	ds_read_b128 v[98:101], v98
	s_waitcnt lgkmcnt(14)
	v_mov_b32_e32 v110, v34
	v_mov_b32_e32 v111, v38
	v_mov_b32_e32 v112, v42
	s_waitcnt lgkmcnt(13)
	v_mov_b32_e32 v113, v46
	s_waitcnt lgkmcnt(12)
	v_mov_b32_e32 v114, v50
	s_waitcnt lgkmcnt(11)
	v_mov_b32_e32 v115, v54
	s_waitcnt lgkmcnt(10)
	v_mov_b32_e32 v116, v58
	s_waitcnt lgkmcnt(9)
	v_mov_b32_e32 v117, v62
	s_waitcnt lgkmcnt(8)
	v_mov_b32_e32 v118, v66
	s_waitcnt lgkmcnt(7)
	v_mov_b32_e32 v119, v70
	s_waitcnt lgkmcnt(6)
	v_mov_b32_e32 v120, v74
	s_waitcnt lgkmcnt(5)
	v_mov_b32_e32 v121, v78
	s_waitcnt lgkmcnt(4)
	v_mov_b32_e32 v122, v82
	s_waitcnt lgkmcnt(3)
	v_mov_b32_e32 v123, v86
	s_waitcnt lgkmcnt(2)
	v_mov_b32_e32 v124, v90
	s_waitcnt lgkmcnt(1)
	v_mov_b32_e32 v125, v94
	v_mov_b32_e32 v38, v35
	v_mov_b32_e32 v46, v43
	v_mov_b32_e32 v54, v51
	v_mov_b32_e32 v62, v59
	v_mov_b32_e32 v70, v67
	v_mov_b32_e32 v78, v75
	v_mov_b32_e32 v86, v83
	v_mov_b32_e32 v94, v91
	v_mov_b32_e32 v34, v36
	v_mov_b32_e32 v35, v40
	v_mov_b32_e32 v42, v44
	v_mov_b32_e32 v43, v48
	v_mov_b32_e32 v50, v52
	v_mov_b32_e32 v51, v56
	v_mov_b32_e32 v58, v60
	v_mov_b32_e32 v59, v64
	v_mov_b32_e32 v66, v68
	v_mov_b32_e32 v67, v72
	v_mov_b32_e32 v74, v76
	v_mov_b32_e32 v75, v80
	v_mov_b32_e32 v82, v84
	v_mov_b32_e32 v83, v88
	v_mov_b32_e32 v90, v92
	v_mov_b32_e32 v91, v96
	v_mov_b32_e32 v40, v37
	v_mov_b32_e32 v48, v45
	v_mov_b32_e32 v56, v53
	v_mov_b32_e32 v64, v61
	v_mov_b32_e32 v72, v69
	v_mov_b32_e32 v80, v77
	v_mov_b32_e32 v88, v85
	v_mov_b32_e32 v96, v93
	s_waitcnt vmcnt(3)
	v_pk_fma_f32 v[16:17], v[186:187], v[110:111], v[16:17] op_sel_hi:[0,1,1]
	v_pk_fma_f32 v[18:19], v[186:187], v[112:113], v[18:19] op_sel_hi:[0,1,1]
	v_pk_fma_f32 v[20:21], v[186:187], v[114:115], v[20:21] op_sel_hi:[0,1,1]
	v_pk_fma_f32 v[22:23], v[186:187], v[116:117], v[22:23] op_sel_hi:[0,1,1]
	v_pk_fma_f32 v[24:25], v[186:187], v[118:119], v[24:25] op_sel_hi:[0,1,1]
	v_pk_fma_f32 v[26:27], v[186:187], v[120:121], v[26:27] op_sel_hi:[0,1,1]
	v_pk_fma_f32 v[28:29], v[186:187], v[122:123], v[28:29] op_sel_hi:[0,1,1]
	v_pk_fma_f32 v[30:31], v[186:187], v[124:125], v[30:31] op_sel_hi:[0,1,1]
	s_waitcnt lgkmcnt(0)
	v_fmac_f32_e32 v0, v186, v98
	s_waitcnt vmcnt(2)
	v_pk_fma_f32 v[16:17], v[186:187], v[38:39], v[16:17] op_sel:[1,0,0] op_sel_hi:[1,1,1]
	v_pk_fma_f32 v[18:19], v[186:187], v[46:47], v[18:19] op_sel:[1,0,0] op_sel_hi:[1,1,1]
	v_pk_fma_f32 v[20:21], v[186:187], v[54:55], v[20:21] op_sel:[1,0,0] op_sel_hi:[1,1,1]
	v_pk_fma_f32 v[22:23], v[186:187], v[62:63], v[22:23] op_sel:[1,0,0] op_sel_hi:[1,1,1]
	v_pk_fma_f32 v[24:25], v[186:187], v[70:71], v[24:25] op_sel:[1,0,0] op_sel_hi:[1,1,1]
	v_pk_fma_f32 v[26:27], v[186:187], v[78:79], v[26:27] op_sel:[1,0,0] op_sel_hi:[1,1,1]
	v_pk_fma_f32 v[28:29], v[186:187], v[86:87], v[28:29] op_sel:[1,0,0] op_sel_hi:[1,1,1]
	v_pk_fma_f32 v[30:31], v[186:187], v[94:95], v[30:31] op_sel:[1,0,0] op_sel_hi:[1,1,1]
	v_fmac_f32_e32 v0, v187, v99
	s_waitcnt vmcnt(1)
	v_pk_fma_f32 v[16:17], v[188:189], v[34:35], v[16:17] op_sel_hi:[0,1,1]
	v_pk_fma_f32 v[18:19], v[188:189], v[42:43], v[18:19] op_sel_hi:[0,1,1]
	v_pk_fma_f32 v[20:21], v[188:189], v[50:51], v[20:21] op_sel_hi:[0,1,1]
	v_pk_fma_f32 v[22:23], v[188:189], v[58:59], v[22:23] op_sel_hi:[0,1,1]
	v_pk_fma_f32 v[24:25], v[188:189], v[66:67], v[24:25] op_sel_hi:[0,1,1]
	v_pk_fma_f32 v[26:27], v[188:189], v[74:75], v[26:27] op_sel_hi:[0,1,1]
	v_pk_fma_f32 v[28:29], v[188:189], v[82:83], v[28:29] op_sel_hi:[0,1,1]
	v_pk_fma_f32 v[30:31], v[188:189], v[90:91], v[30:31] op_sel_hi:[0,1,1]
	v_fmac_f32_e32 v0, v188, v100
	s_waitcnt vmcnt(0)
	v_pk_fma_f32 v[16:17], v[188:189], v[40:41], v[16:17] op_sel:[1,0,0] op_sel_hi:[1,1,1]
	v_pk_fma_f32 v[18:19], v[188:189], v[48:49], v[18:19] op_sel:[1,0,0] op_sel_hi:[1,1,1]
	v_pk_fma_f32 v[20:21], v[188:189], v[56:57], v[20:21] op_sel:[1,0,0] op_sel_hi:[1,1,1]
	v_pk_fma_f32 v[22:23], v[188:189], v[64:65], v[22:23] op_sel:[1,0,0] op_sel_hi:[1,1,1]
	v_pk_fma_f32 v[24:25], v[188:189], v[72:73], v[24:25] op_sel:[1,0,0] op_sel_hi:[1,1,1]
	v_pk_fma_f32 v[26:27], v[188:189], v[80:81], v[26:27] op_sel:[1,0,0] op_sel_hi:[1,1,1]
	v_pk_fma_f32 v[28:29], v[188:189], v[88:89], v[28:29] op_sel:[1,0,0] op_sel_hi:[1,1,1]
	v_pk_fma_f32 v[30:31], v[188:189], v[96:97], v[30:31] op_sel:[1,0,0] op_sel_hi:[1,1,1]
	v_fmac_f32_e32 v0, v189, v101
	ds_write2_b32 v4, v16, v17 offset1:32
	ds_write2_b32 v4, v18, v19 offset0:64 offset1:96
	ds_write2_b32 v4, v20, v21 offset0:128 offset1:160
	ds_write2_b32 v4, v22, v23 offset0:192 offset1:224
	ds_write2_b32 v33, v24, v25 offset1:32
	ds_write2_b32 v33, v26, v27 offset0:64 offset1:96
	ds_write2_b32 v33, v28, v29 offset0:128 offset1:160
	ds_write2_b32 v33, v30, v31 offset0:192 offset1:224
	ds_write_b32 v4, v0 offset:2048
	s_waitcnt lgkmcnt(0)
	s_barrier
	s_and_saveexec_b64 s[10:11], s[4:5]
	s_cbranch_execz .LBB0_19
	s_mul_i32 s0, s19, 0xc00
	s_add_i32 s0, s0, s8
	v_or_b32_e32 v14, s0, v32
	v_ashrrev_i32_e32 v15, 31, v14
	s_mul_i32 s19, s19, 17
	v_lshl_add_u64 v[14:15], v[14:15], 2, s[62:63]
	v_lshl_add_u64 v[16:17], s[8:9], 2, v[6:7]
	s_mov_b64 s[8:9], 0
	v_mov_b32_e32 v0, v10
